# plus: fused-epilogue slot reads as two 16B loads; GU epilogue re-emitted with packed f32 ops, 8 elements in flight; IN natural-layout stores merged to 16B via permlane16_swap
# speedup vs baseline: 1.0184x; 1.0148x over previous
; #define PG8_STAGE(bufoff, gbase, voff) do { _Pragma("unroll") for (int _i = 0; _i < 2; ++_i) \
;         __builtin_amdgcn_global_load_lds((const unsigned*)((const char*)(gbase) + (voff)[_i]), (LAS unsigned*)(lds + (bufoff) + ldsw + _i * 8192), 16, 0, 0); } while (0)
; #define PG8_LDA(dst, b, h) do { _Pragma("unroll") for (int m = 0; m < 4; ++m) _Pragma("unroll") for (int k = 0; k < 2; ++k) dst[m][k] = *(const LAS bf16x8*)(lds + PG8_SA(b, h) + aoff + m * 2048 + k * 1024); } while (0)
; #define PG8_LDB(dst, b, h) do { _Pragma("unroll") for (int n = 0; n < 2; ++n) _Pragma("unroll") for (int k = 0; k < 2; ++k) dst[n][k] = *(const LAS bf16x8*)(lds + PG8_SB(b, h) + boff + n * 2048 + k * 1024); } while (0)
; #define PG8_MMA(ai, bj, At, Bt) do { __builtin_amdgcn_s_setprio(1); _Pragma("unroll") for (int m = 0; m < 4; ++m) _Pragma("unroll") for (int n = 0; n < 2; ++n) _Pragma("unroll") for (int k = 0; k < 2; ++k) \
;         acc[ai][bj][m][n] = __builtin_amdgcn_mfma_f32_16x16x32_bf16(Bt[n][k], At[m][k], acc[ai][bj][m][n], 0, 0, 0); __builtin_amdgcn_s_setprio(0); } while (0)
; #define PG8_WAIT_V(n) asm volatile("s_waitcnt vmcnt(" #n ")" ::: "memory")
; #define PG8_WAIT_L(n) asm volatile("s_waitcnt lgkmcnt(" #n ")" ::: "memory")
; #define PG8_BAR __builtin_amdgcn_s_barrier()
; #define PG8_SCHED __builtin_amdgcn_sched_barrier(0)
; template <class Epi>
; __device__ __forceinline__ void gemm_phase(LAS unsigned char* lds, const Gemm g, const Order& S, KP kp, int code, int wv) {
;     ...
;             PG8_LDB(B0, 0, 0); PG8_SCHED; PG8_LDA(At, 0, 0); PG8_STAGE(PG8_SA(1, 1), a1 + hstepA, voffA);
;             PG8_WAIT_L(8); PG8_BAR; PG8_WAIT_L(0); PG8_MMA(0, 0, At, B0); PG8_BAR; PG8_SCHED;
;             PG8_LDB(B1, 0, 1); PG8_STAGE(PG8_SB(0, 0), b2, voffB);
;             PG8_BAR; PG8_WAIT_L(0); PG8_MMA(0, 1, At, B1); PG8_BAR;
;             PG8_LDA(At, 0, 1); PG8_STAGE(PG8_SA(0, 0), a2, voffA);
;             PG8_BAR; PG8_WAIT_L(0); PG8_MMA(1, 0, At, B0); PG8_BAR; PG8_SCHED;
;             PG8_STAGE(PG8_SB(0, 1), b2 + hstepB, voffB);
;             PG8_WAIT_V(6); PG8_BAR; PG8_MMA(1, 1, At, B1); PG8_BAR;
;             PG8_LDB(B0, 1, 0); PG8_SCHED; PG8_LDA(At, 1, 0); PG8_STAGE(PG8_SA(0, 1), a2 + hstepA, voffA);
;             PG8_WAIT_L(8); PG8_BAR; PG8_WAIT_L(0); PG8_MMA(0, 0, At, B0); PG8_BAR; PG8_SCHED;
.LBB0_136:
	s_add_u32 s6, s4, 0xfff80080
	s_addc_u32 s7, s5, -1
	s_add_i32 s19, 0, 0x10000
	v_add_u32_e32 v0, s19, v145
	ds_read_b128 v[130:133], v0
	ds_read_b128 v[134:137], v0 offset:1024
	ds_read_b128 v[154:157], v0 offset:2048
	ds_read_b128 v[158:161], v0 offset:3072
	s_cmp_eq_u32 s17, 28
	s_cselect_b32 s9, s0, s7
	s_cselect_b32 s8, s1, s6
	s_cselect_b32 s7, s12, s15
	s_cselect_b32 s6, s13, s14
	v_lshl_add_u64 v[212:213], s[4:5], 0, v[150:151]
	s_add_i32 m0, s30, 0xc000
	ds_read_b128 v[184:187], v149
	ds_read_b128 v[188:191], v149 offset:1024
	ds_read_b128 v[192:195], v149 offset:2048
	ds_read_b128 v[196:199], v149 offset:3072
	ds_read_b128 v[200:203], v149 offset:4096
	ds_read_b128 v[204:207], v149 offset:5120
	ds_read_b128 v[208:211], v149 offset:6144
	ds_read_b128 v[224:227], v149 offset:7168
	global_load_lds_dwordx4 v[212:213], off
	v_lshl_add_u64 v[212:213], s[4:5], 0, v[152:153]
	s_add_i32 m0, s30, 0xe000
	s_nop 0
	global_load_lds_dwordx4 v[212:213], off
	s_waitcnt lgkmcnt(8)
	s_barrier
	s_waitcnt lgkmcnt(0)
	s_setprio 1
	s_waitcnt lgkmcnt(0)
	v_mfma_f32_16x16x32_bf16 v[122:125], v[130:133], v[184:187], v[122:125]
	v_mfma_f32_16x16x32_bf16 v[126:129], v[154:157], v[184:187], v[126:129]
	v_mfma_f32_16x16x32_bf16 v[110:113], v[130:133], v[192:195], v[110:113]
	v_mfma_f32_16x16x32_bf16 v[106:109], v[154:157], v[192:195], v[106:109]
	v_mfma_f32_16x16x32_bf16 v[94:97], v[130:133], v[200:203], v[94:97]
	v_mfma_f32_16x16x32_bf16 v[90:93], v[154:157], v[200:203], v[90:93]
	v_mfma_f32_16x16x32_bf16 v[78:81], v[130:133], v[208:211], v[78:81]
	v_mfma_f32_16x16x32_bf16 v[74:77], v[154:157], v[208:211], v[74:77]
	v_mfma_f32_16x16x32_bf16 v[122:125], v[134:137], v[188:191], v[122:125]
	v_mfma_f32_16x16x32_bf16 v[126:129], v[158:161], v[188:191], v[126:129]
	v_mfma_f32_16x16x32_bf16 v[110:113], v[134:137], v[196:199], v[110:113]
	v_mfma_f32_16x16x32_bf16 v[106:109], v[158:161], v[196:199], v[106:109]
	v_mfma_f32_16x16x32_bf16 v[94:97], v[134:137], v[204:207], v[94:97]
	v_mfma_f32_16x16x32_bf16 v[90:93], v[158:161], v[204:207], v[90:93]
	v_mfma_f32_16x16x32_bf16 v[78:81], v[134:137], v[224:227], v[78:81]
	v_mfma_f32_16x16x32_bf16 v[74:77], v[158:161], v[224:227], v[74:77]
	s_setprio 0
	s_barrier
	s_add_i32 s26, 0, 0x14000
	s_add_i32 s19, s19, s29
	v_add_u32_e32 v0, s26, v145
	v_lshl_add_u64 v[212:213], s[6:7], 0, v[140:141]
	s_mov_b32 m0, s19
	ds_read_b128 v[228:231], v0
	ds_read_b128 v[232:235], v0 offset:1024
	ds_read_b128 v[236:239], v0 offset:2048
	ds_read_b128 v[240:243], v0 offset:3072
	global_load_lds_dwordx4 v[212:213], off
	v_lshl_add_u64 v[214:215], s[6:7], 0, v[138:139]
	s_add_i32 m0, s19, 0x2000
	s_nop 0
	global_load_lds_dwordx4 v[214:215], off
	s_barrier
	s_waitcnt lgkmcnt(0)
	s_setprio 1
	s_waitcnt lgkmcnt(0)
	v_mfma_f32_16x16x32_bf16 v[118:121], v[228:231], v[184:187], v[118:121]
	v_mfma_f32_16x16x32_bf16 v[114:117], v[236:239], v[184:187], v[114:117]
	v_mfma_f32_16x16x32_bf16 v[102:105], v[228:231], v[192:195], v[102:105]
	v_mfma_f32_16x16x32_bf16 v[98:101], v[236:239], v[192:195], v[98:101]
	v_mfma_f32_16x16x32_bf16 v[86:89], v[228:231], v[200:203], v[86:89]
	v_mfma_f32_16x16x32_bf16 v[82:85], v[236:239], v[200:203], v[82:85]
	v_mfma_f32_16x16x32_bf16 v[70:73], v[228:231], v[208:211], v[70:73]
	v_mfma_f32_16x16x32_bf16 v[66:69], v[236:239], v[208:211], v[66:69]
	v_mfma_f32_16x16x32_bf16 v[118:121], v[232:235], v[188:191], v[118:121]
	v_mfma_f32_16x16x32_bf16 v[114:117], v[240:243], v[188:191], v[114:117]
	v_mfma_f32_16x16x32_bf16 v[102:105], v[232:235], v[196:199], v[102:105]
	v_mfma_f32_16x16x32_bf16 v[98:101], v[240:243], v[196:199], v[98:101]
	v_mfma_f32_16x16x32_bf16 v[86:89], v[232:235], v[204:207], v[86:89]
	v_mfma_f32_16x16x32_bf16 v[82:85], v[240:243], v[204:207], v[82:85]
	v_mfma_f32_16x16x32_bf16 v[70:73], v[232:235], v[224:227], v[70:73]
	v_mfma_f32_16x16x32_bf16 v[66:69], v[240:243], v[224:227], v[66:69]
	s_setprio 0
	s_mov_b32 m0, s30
	v_lshl_add_u64 v[218:219], s[8:9], 0, v[140:141]
	s_barrier
	ds_read_b128 v[184:187], v149 offset:16384
	ds_read_b128 v[188:191], v149 offset:17408
	ds_read_b128 v[192:195], v149 offset:18432
	ds_read_b128 v[196:199], v149 offset:19456
	ds_read_b128 v[200:203], v149 offset:20480
	ds_read_b128 v[204:207], v149 offset:21504
	ds_read_b128 v[208:211], v149 offset:22528
	ds_read_b128 v[224:227], v149 offset:23552
	global_load_lds_dwordx4 v[218:219], off
	v_lshl_add_u64 v[244:245], s[8:9], 0, v[138:139]
	s_mov_b32 m0, s31
	s_nop 0
	global_load_lds_dwordx4 v[244:245], off
	s_barrier
	s_waitcnt lgkmcnt(0)
	s_setprio 1
	s_waitcnt lgkmcnt(0)
	v_mfma_f32_16x16x32_bf16 v[62:65], v[130:133], v[184:187], v[62:65]
	v_mfma_f32_16x16x32_bf16 v[58:61], v[154:157], v[184:187], v[58:61]
	v_mfma_f32_16x16x32_bf16 v[46:49], v[130:133], v[192:195], v[46:49]
	v_mfma_f32_16x16x32_bf16 v[42:45], v[154:157], v[192:195], v[42:45]
	v_mfma_f32_16x16x32_bf16 v[30:33], v[130:133], v[200:203], v[30:33]
	v_mfma_f32_16x16x32_bf16 v[26:29], v[154:157], v[200:203], v[26:29]
	v_mfma_f32_16x16x32_bf16 v[14:17], v[130:133], v[208:211], v[14:17]
	v_mfma_f32_16x16x32_bf16 v[10:13], v[154:157], v[208:211], v[10:13]
	v_mfma_f32_16x16x32_bf16 v[62:65], v[134:137], v[188:191], v[62:65]
	v_mfma_f32_16x16x32_bf16 v[58:61], v[158:161], v[188:191], v[58:61]
	v_mfma_f32_16x16x32_bf16 v[46:49], v[134:137], v[196:199], v[46:49]
	v_mfma_f32_16x16x32_bf16 v[42:45], v[158:161], v[196:199], v[42:45]
	v_mfma_f32_16x16x32_bf16 v[30:33], v[134:137], v[204:207], v[30:33]
	v_mfma_f32_16x16x32_bf16 v[26:29], v[158:161], v[204:207], v[26:29]
	v_mfma_f32_16x16x32_bf16 v[14:17], v[134:137], v[224:227], v[14:17]
	v_mfma_f32_16x16x32_bf16 v[10:13], v[158:161], v[224:227], v[10:13]
	s_setprio 0
	s_barrier
; #define PG8_STAGE(bufoff, gbase, voff) do { _Pragma("unroll") for (int _i = 0; _i < 2; ++_i) \
;         __builtin_amdgcn_global_load_lds((const unsigned*)((const char*)(gbase) + (voff)[_i]), (LAS unsigned*)(lds + (bufoff) + ldsw + _i * 8192), 16, 0, 0); } while (0)
; #define PG8_LDA(dst, b, h) do { _Pragma("unroll") for (int m = 0; m < 4; ++m) _Pragma("unroll") for (int k = 0; k < 2; ++k) dst[m][k] = *(const LAS bf16x8*)(lds + PG8_SA(b, h) + aoff + m * 2048 + k * 1024); } while (0)
; #define PG8_LDB(dst, b, h) do { _Pragma("unroll") for (int n = 0; n < 2; ++n) _Pragma("unroll") for (int k = 0; k < 2; ++k) dst[n][k] = *(const LAS bf16x8*)(lds + PG8_SB(b, h) + boff + n * 2048 + k * 1024); } while (0)
; #define PG8_MMA(ai, bj, At, Bt) do { __builtin_amdgcn_s_setprio(1); _Pragma("unroll") for (int m = 0; m < 4; ++m) _Pragma("unroll") for (int n = 0; n < 2; ++n) _Pragma("unroll") for (int k = 0; k < 2; ++k) \
;         acc[ai][bj][m][n] = __builtin_amdgcn_mfma_f32_16x16x32_bf16(Bt[n][k], At[m][k], acc[ai][bj][m][n], 0, 0, 0); __builtin_amdgcn_s_setprio(0); } while (0)
; #define PG8_WAIT_V(n) asm volatile("s_waitcnt vmcnt(" #n ")" ::: "memory")
; #define PG8_WAIT_L(n) asm volatile("s_waitcnt lgkmcnt(" #n ")" ::: "memory")
; #define PG8_BAR __builtin_amdgcn_s_barrier()
; #define PG8_SCHED __builtin_amdgcn_sched_barrier(0)
; template <class Epi>
; __device__ __forceinline__ void gemm_phase(LAS unsigned char* lds, const Gemm g, const Order& S, KP kp, int code, int wv) {
;     ...
;             PG8_STAGE(PG8_SB(0, 1), b2 + hstepB, voffB);
;             PG8_WAIT_V(6); PG8_BAR; PG8_MMA(1, 1, At, B1); PG8_BAR;
;             PG8_LDB(B0, 1, 0); PG8_SCHED; PG8_LDA(At, 1, 0); PG8_STAGE(PG8_SA(0, 1), a2 + hstepA, voffA);
;             PG8_WAIT_L(8); PG8_BAR; PG8_WAIT_L(0); PG8_MMA(0, 0, At, B0); PG8_BAR; PG8_SCHED;
;             PG8_LDB(B1, 1, 1); PG8_STAGE(PG8_SB(1, 0), b3, voffB);
;             PG8_BAR; PG8_WAIT_L(0); PG8_MMA(0, 1, At, B1); PG8_BAR;
;             PG8_LDA(At, 1, 1); PG8_STAGE(PG8_SA(1, 0), a3, voffA);
;             PG8_BAR; PG8_WAIT_L(0); PG8_MMA(1, 0, At, B0); PG8_BAR; PG8_SCHED;
;             PG8_STAGE(PG8_SB(1, 1), b3 + hstepB, voffB);
;             PG8_WAIT_V(6); PG8_BAR; PG8_MMA(1, 1, At, B1); PG8_BAR;
	s_add_u32 s24, s6, 0x80000
	s_addc_u32 s25, s7, 0
	s_add_i32 s19, s26, s29
	v_lshl_add_u64 v[130:131], s[24:25], 0, v[140:141]
	s_mov_b32 m0, s19
	s_nop 0
	global_load_lds_dwordx4 v[130:131], off
	v_lshl_add_u64 v[130:131], s[24:25], 0, v[138:139]
	s_add_i32 m0, s19, 0x2000
	s_nop 0
	global_load_lds_dwordx4 v[130:131], off
	s_waitcnt vmcnt(6)
	s_barrier
	s_setprio 1
	v_mfma_f32_16x16x32_bf16 v[54:57], v[228:231], v[184:187], v[54:57]
	v_mfma_f32_16x16x32_bf16 v[50:53], v[236:239], v[184:187], v[50:53]
	v_mfma_f32_16x16x32_bf16 v[38:41], v[228:231], v[192:195], v[38:41]
	v_mfma_f32_16x16x32_bf16 v[34:37], v[236:239], v[192:195], v[34:37]
	v_mfma_f32_16x16x32_bf16 v[22:25], v[228:231], v[200:203], v[22:25]
	v_mfma_f32_16x16x32_bf16 v[18:21], v[236:239], v[200:203], v[18:21]
	v_mfma_f32_16x16x32_bf16 v[6:9], v[228:231], v[208:211], v[6:9]
	v_mfma_f32_16x16x32_bf16 v[2:5], v[236:239], v[208:211], v[2:5]
	v_mfma_f32_16x16x32_bf16 v[54:57], v[232:235], v[188:191], v[54:57]
	v_mfma_f32_16x16x32_bf16 v[50:53], v[240:243], v[188:191], v[50:53]
	v_mfma_f32_16x16x32_bf16 v[38:41], v[232:235], v[196:199], v[38:41]
	v_mfma_f32_16x16x32_bf16 v[34:37], v[240:243], v[196:199], v[34:37]
	v_mfma_f32_16x16x32_bf16 v[22:25], v[232:235], v[204:207], v[22:25]
	v_mfma_f32_16x16x32_bf16 v[18:21], v[240:243], v[204:207], v[18:21]
	v_mfma_f32_16x16x32_bf16 v[6:9], v[232:235], v[224:227], v[6:9]
	v_mfma_f32_16x16x32_bf16 v[2:5], v[240:243], v[224:227], v[2:5]
	s_setprio 0
	s_add_i32 s19, 0, 0x18000
	v_add_u32_e32 v0, s19, v145
	s_barrier
	ds_read_b128 v[130:133], v0
	ds_read_b128 v[134:137], v0 offset:1024
	ds_read_b128 v[154:157], v0 offset:2048
	ds_read_b128 v[158:161], v0 offset:3072
	s_add_u32 s8, s8, 0x80000
	s_addc_u32 s9, s9, 0
	s_mov_b32 m0, s34
	v_lshl_add_u64 v[228:229], s[8:9], 0, v[140:141]
	ds_read_b128 v[184:187], v149 offset:32768
	ds_read_b128 v[188:191], v149 offset:33792
	ds_read_b128 v[192:195], v149 offset:34816
	ds_read_b128 v[196:199], v149 offset:35840
	ds_read_b128 v[200:203], v149 offset:36864
	ds_read_b128 v[204:207], v149 offset:37888
	ds_read_b128 v[208:211], v149 offset:38912
	ds_read_b128 v[224:227], v149 offset:39936
	global_load_lds_dwordx4 v[228:229], off
	v_lshl_add_u64 v[228:229], s[8:9], 0, v[138:139]
	s_mov_b32 m0, s35
	s_nop 0
	global_load_lds_dwordx4 v[228:229], off
	s_waitcnt lgkmcnt(8)
	s_barrier
	s_waitcnt lgkmcnt(0)
	s_setprio 1
	s_waitcnt lgkmcnt(0)
	v_mfma_f32_16x16x32_bf16 v[122:125], v[130:133], v[184:187], v[122:125]
	v_mfma_f32_16x16x32_bf16 v[126:129], v[154:157], v[184:187], v[126:129]
	v_mfma_f32_16x16x32_bf16 v[110:113], v[130:133], v[192:195], v[110:113]
	v_mfma_f32_16x16x32_bf16 v[106:109], v[154:157], v[192:195], v[106:109]
	v_mfma_f32_16x16x32_bf16 v[94:97], v[130:133], v[200:203], v[94:97]
	v_mfma_f32_16x16x32_bf16 v[90:93], v[154:157], v[200:203], v[90:93]
	v_mfma_f32_16x16x32_bf16 v[78:81], v[130:133], v[208:211], v[78:81]
	v_mfma_f32_16x16x32_bf16 v[74:77], v[154:157], v[208:211], v[74:77]
	v_mfma_f32_16x16x32_bf16 v[122:125], v[134:137], v[188:191], v[122:125]
	v_mfma_f32_16x16x32_bf16 v[126:129], v[158:161], v[188:191], v[126:129]
	v_mfma_f32_16x16x32_bf16 v[110:113], v[134:137], v[196:199], v[110:113]
	v_mfma_f32_16x16x32_bf16 v[106:109], v[158:161], v[196:199], v[106:109]
	v_mfma_f32_16x16x32_bf16 v[94:97], v[134:137], v[204:207], v[94:97]
	v_mfma_f32_16x16x32_bf16 v[90:93], v[158:161], v[204:207], v[90:93]
	v_mfma_f32_16x16x32_bf16 v[78:81], v[134:137], v[224:227], v[78:81]
	v_mfma_f32_16x16x32_bf16 v[74:77], v[158:161], v[224:227], v[74:77]
	s_setprio 0
	s_barrier
	s_add_i32 s8, 0, 0x1c000
	s_add_i32 s9, s19, s29
	v_add_u32_e32 v0, s8, v145
	v_lshl_add_u64 v[212:213], v[212:213], 0, s[70:71]
	s_mov_b32 m0, s9
	ds_read_b128 v[228:231], v0
	ds_read_b128 v[232:235], v0 offset:1024
	ds_read_b128 v[236:239], v0 offset:2048
	ds_read_b128 v[240:243], v0 offset:3072
	global_load_lds_dwordx4 v[212:213], off
	v_lshl_add_u64 v[212:213], v[214:215], 0, s[70:71]
	s_add_i32 m0, s9, 0x2000
	s_nop 0
	global_load_lds_dwordx4 v[212:213], off
	s_barrier
	s_waitcnt lgkmcnt(0)
	s_setprio 1
	s_waitcnt lgkmcnt(0)
	v_mfma_f32_16x16x32_bf16 v[118:121], v[228:231], v[184:187], v[118:121]
	v_mfma_f32_16x16x32_bf16 v[114:117], v[236:239], v[184:187], v[114:117]
	v_mfma_f32_16x16x32_bf16 v[102:105], v[228:231], v[192:195], v[102:105]
	v_mfma_f32_16x16x32_bf16 v[98:101], v[236:239], v[192:195], v[98:101]
	v_mfma_f32_16x16x32_bf16 v[86:89], v[228:231], v[200:203], v[86:89]
	v_mfma_f32_16x16x32_bf16 v[82:85], v[236:239], v[200:203], v[82:85]
	v_mfma_f32_16x16x32_bf16 v[70:73], v[228:231], v[208:211], v[70:73]
	v_mfma_f32_16x16x32_bf16 v[66:69], v[236:239], v[208:211], v[66:69]
	v_mfma_f32_16x16x32_bf16 v[118:121], v[232:235], v[188:191], v[118:121]
	v_mfma_f32_16x16x32_bf16 v[114:117], v[240:243], v[188:191], v[114:117]
	v_mfma_f32_16x16x32_bf16 v[102:105], v[232:235], v[196:199], v[102:105]
	v_mfma_f32_16x16x32_bf16 v[98:101], v[240:243], v[196:199], v[98:101]
	v_mfma_f32_16x16x32_bf16 v[86:89], v[232:235], v[204:207], v[86:89]
	v_mfma_f32_16x16x32_bf16 v[82:85], v[240:243], v[204:207], v[82:85]
	v_mfma_f32_16x16x32_bf16 v[70:73], v[232:235], v[224:227], v[70:73]
	v_mfma_f32_16x16x32_bf16 v[66:69], v[240:243], v[224:227], v[66:69]
	s_setprio 0
	s_mov_b32 m0, s36
	v_lshl_add_u64 v[212:213], v[218:219], 0, s[70:71]
	s_barrier
	ds_read_b128 v[184:187], v149 offset:49152
	ds_read_b128 v[188:191], v149 offset:50176
	ds_read_b128 v[192:195], v149 offset:51200
	ds_read_b128 v[196:199], v149 offset:52224
	ds_read_b128 v[200:203], v149 offset:53248
	ds_read_b128 v[204:207], v149 offset:54272
	ds_read_b128 v[208:211], v149 offset:55296
	ds_read_b128 v[224:227], v149 offset:56320
	global_load_lds_dwordx4 v[212:213], off
	v_lshl_add_u64 v[212:213], v[244:245], 0, s[70:71]
	s_mov_b32 m0, s37
	s_nop 0
	global_load_lds_dwordx4 v[212:213], off
	s_barrier
; #define PG8_STAGE(bufoff, gbase, voff) do { _Pragma("unroll") for (int _i = 0; _i < 2; ++_i) \
;         __builtin_amdgcn_global_load_lds((const unsigned*)((const char*)(gbase) + (voff)[_i]), (LAS unsigned*)(lds + (bufoff) + ldsw + _i * 8192), 16, 0, 0); } while (0)
; #define PG8_MMA(ai, bj, At, Bt) do { __builtin_amdgcn_s_setprio(1); _Pragma("unroll") for (int m = 0; m < 4; ++m) _Pragma("unroll") for (int n = 0; n < 2; ++n) _Pragma("unroll") for (int k = 0; k < 2; ++k) \
;         acc[ai][bj][m][n] = __builtin_amdgcn_mfma_f32_16x16x32_bf16(Bt[n][k], At[m][k], acc[ai][bj][m][n], 0, 0, 0); __builtin_amdgcn_s_setprio(0); } while (0)
; #define PG8_WAIT_V(n) asm volatile("s_waitcnt vmcnt(" #n ")" ::: "memory")
; #define PG8_WAIT_L(n) asm volatile("s_waitcnt lgkmcnt(" #n ")" ::: "memory")
; #define PG8_BAR __builtin_amdgcn_s_barrier()
; #define PG8_SCHED __builtin_amdgcn_sched_barrier(0)
;     __device__ __forceinline__ void operator()(const f32x4 (&acc)[2][2][4][2], const Unit& u, int wr, int wc, int fr, int fq) const {
;         const int pm = u.pm, pn = u.pn;
;         const bool ctx = pm >= 32;
;         const int rbase = pm * BM + wr * 64 + fr;
;         const int b = ctx ? pm - 32 : (pm >> 3);
;         const int ccb = ctx ? 0 : 2 + 2 * (pm & 7);
;         if (pn < 8) {
; template <class Epi>
; __device__ __forceinline__ void gemm_phase(LAS unsigned char* lds, const Gemm g, const Order& S, KP kp, int code, int wv) {
;     ...
;             PG8_BAR; PG8_WAIT_L(0); PG8_MMA(1, 0, At, B0); PG8_BAR; PG8_SCHED;
;             PG8_STAGE(PG8_SB(1, 1), b3 + hstepB, voffB);
;             PG8_WAIT_V(6); PG8_BAR; PG8_MMA(1, 1, At, B1); PG8_BAR;
;         }
;         if (!Epi::HAS_FUSED || (code & 8)) { KP kq = kp; asm volatile("" : "+s"(kq)); const Epi E = Epi::make(kq, code); E(acc, cur, wr, wc, fr, fq); }
	s_waitcnt lgkmcnt(0)
	s_setprio 1
	s_waitcnt lgkmcnt(0)
	v_mfma_f32_16x16x32_bf16 v[62:65], v[130:133], v[184:187], v[62:65]
	v_mfma_f32_16x16x32_bf16 v[58:61], v[154:157], v[184:187], v[58:61]
	v_mfma_f32_16x16x32_bf16 v[46:49], v[130:133], v[192:195], v[46:49]
	v_mfma_f32_16x16x32_bf16 v[42:45], v[154:157], v[192:195], v[42:45]
	v_mfma_f32_16x16x32_bf16 v[30:33], v[130:133], v[200:203], v[30:33]
	v_mfma_f32_16x16x32_bf16 v[26:29], v[154:157], v[200:203], v[26:29]
	v_mfma_f32_16x16x32_bf16 v[14:17], v[130:133], v[208:211], v[14:17]
	v_mfma_f32_16x16x32_bf16 v[10:13], v[154:157], v[208:211], v[10:13]
	v_mfma_f32_16x16x32_bf16 v[62:65], v[134:137], v[188:191], v[62:65]
	v_mfma_f32_16x16x32_bf16 v[58:61], v[158:161], v[188:191], v[58:61]
	v_mfma_f32_16x16x32_bf16 v[46:49], v[134:137], v[196:199], v[46:49]
	v_mfma_f32_16x16x32_bf16 v[42:45], v[158:161], v[196:199], v[42:45]
	v_mfma_f32_16x16x32_bf16 v[30:33], v[134:137], v[204:207], v[30:33]
	v_mfma_f32_16x16x32_bf16 v[26:29], v[158:161], v[204:207], v[26:29]
	v_mfma_f32_16x16x32_bf16 v[14:17], v[134:137], v[224:227], v[14:17]
	v_mfma_f32_16x16x32_bf16 v[10:13], v[158:161], v[224:227], v[10:13]
	s_setprio 0
	s_barrier
	s_add_u32 s6, s6, 0x80080
	s_addc_u32 s7, s7, 0
	s_add_i32 s8, s8, s29
	v_lshl_add_u64 v[130:131], s[6:7], 0, v[140:141]
	s_mov_b32 m0, s8
	s_nop 0
	global_load_lds_dwordx4 v[130:131], off
	v_lshl_add_u64 v[130:131], s[6:7], 0, v[138:139]
	s_add_i32 m0, s8, 0x2000
	s_nop 0
	global_load_lds_dwordx4 v[130:131], off
	s_waitcnt vmcnt(6)
	s_barrier
	s_setprio 1
	v_mfma_f32_16x16x32_bf16 v[54:57], v[228:231], v[184:187], v[54:57]
	v_mfma_f32_16x16x32_bf16 v[50:53], v[236:239], v[184:187], v[50:53]
	v_mfma_f32_16x16x32_bf16 v[38:41], v[228:231], v[192:195], v[38:41]
	v_mfma_f32_16x16x32_bf16 v[34:37], v[236:239], v[192:195], v[34:37]
	v_mfma_f32_16x16x32_bf16 v[22:25], v[228:231], v[200:203], v[22:25]
	v_mfma_f32_16x16x32_bf16 v[18:21], v[236:239], v[200:203], v[18:21]
	v_mfma_f32_16x16x32_bf16 v[6:9], v[228:231], v[208:211], v[6:9]
	v_mfma_f32_16x16x32_bf16 v[2:5], v[236:239], v[208:211], v[2:5]
	v_mfma_f32_16x16x32_bf16 v[54:57], v[232:235], v[188:191], v[54:57]
	v_mfma_f32_16x16x32_bf16 v[50:53], v[240:243], v[188:191], v[50:53]
	v_mfma_f32_16x16x32_bf16 v[38:41], v[232:235], v[196:199], v[38:41]
	v_mfma_f32_16x16x32_bf16 v[34:37], v[240:243], v[196:199], v[34:37]
	v_mfma_f32_16x16x32_bf16 v[22:25], v[232:235], v[204:207], v[22:25]
	v_mfma_f32_16x16x32_bf16 v[18:21], v[240:243], v[204:207], v[18:21]
	v_mfma_f32_16x16x32_bf16 v[6:9], v[232:235], v[224:227], v[6:9]
	v_mfma_f32_16x16x32_bf16 v[2:5], v[240:243], v[224:227], v[2:5]
	s_setprio 0
	s_add_i32 s17, s17, 2
	s_add_u32 s4, s4, 0x100
	s_addc_u32 s5, s5, 0
	s_add_u32 s14, s14, 0x100
	s_addc_u32 s15, s15, 0
	s_cmp_gt_u32 s17, 29
	s_barrier
	s_cbranch_scc0 .LBB0_136
	v_mbcnt_lo_u32_b32 v180, -1, 0
	v_mbcnt_hi_u32_b32 v180, -1, v180
	v_bfe_u32 v180, v180, 4, 1
	v_mul_u32_u24_e32 v180, 24, v180
	v_mov_b32_e32 v181, 0
	v_mbcnt_lo_u32_b32 v164, -1, 0
	v_mbcnt_hi_u32_b32 v164, -1, v164
	v_and_b32_e32 v166, 3, v164
	v_mul_u32_u24_e32 v166, 0xfe, v166
	v_mov_b32_e32 v167, 0
	v_and_b32_e32 v164, 1, v164
	v_cmp_eq_u32_e64 s[98:99], 0, v164
	v_mov_b32_e32 v165, 0x3020706
	v_mov_b32_e32 v170, 0x5040100
	s_nop 1
	v_cndmask_b32_e64 v165, v165, v170, s[98:99]
	s_mov_b32 s98, 0xcccccccc
	s_mov_b32 s99, 0xcccccccc
	s_mov_b64 s[0:1], s[78:79]
	s_cmp_lt_i32 s10, 32
	s_load_dwordx2 s[24:25], s[0:1], 0xc0
	s_cselect_b64 s[6:7], -1, 0
	s_lshl_b32 s4, s10, 1
	s_and_b32 s4, s4, 14
	s_sub_i32 s0, s10, 32
	s_ashr_i32 s1, s10, 3
	s_add_i32 s4, s4, 2
	s_cmp_gt_i32 s10, 31
	v_lshl_add_u32 v154, s10, 8, v142
	s_cselect_b32 s8, s0, s1
	s_cselect_b32 s10, 0, s4
	s_cmp_gt_i32 s11, 7
	s_mov_b64 s[0:1], -1
	s_cbranch_scc0 .LBB0_143
	s_cmp_gt_u32 s11, 11
	s_cbranch_scc0 .LBB0_140
; __device__ __forceinline__ unsigned cvt_pk_bf16(float lo, float hi) { unsigned r; asm("v_cvt_pk_bf16_f32 %0, %1, %2" : "=v"(r) : "v"(lo), "v"(hi)); return r; }
;     __device__ __forceinline__ void operator()(const f32x4 (&acc)[2][2][4][2], const Unit& u, int wr, int wc, int fr, int fq) const {
;     ...
;             const int col0 = (pn - 12) * BM + wc * 32 + 4 * fq;
; #pragma unroll
;             for (int ai = 0; ai < 2; ++ai)
; #pragma unroll
;                 for (int m = 0; m < 4; ++m) {
;                     bf16_t* rowp = pr + (size_t)(rbase + ai * HALF + m * 16) * 4096 + col0;
; #pragma unroll
;                     for (int bj = 0; bj < 2; ++bj)
; #pragma unroll
;                         for (int n = 0; n < 2; ++n) {
;                             const f32x4 x = acc[ai][bj][m][n];
;                             u32x2 w; w.x = cvt_pk_bf16(x[0], x[1]); w.y = cvt_pk_bf16(x[2], x[3]);
;                             *(u32x2*)(rowp + bj * HALF + n * 16) = w;
;                         }
;                 }
	s_waitcnt lgkmcnt(0)
	s_add_u32 s4, s24, 0x242b4000
	v_ashrrev_i32_e32 v155, 31, v154
	s_addc_u32 s5, s25, 0
	v_lshl_add_u32 v0, s11, 8, v147
	v_lshlrev_b64 v[130:131], 13, v[154:155]
	v_lshl_add_u64 v[130:131], s[4:5], 0, v[130:131]
	v_lshlrev_b64 v[132:133], 1, v[0:1]
	v_lshl_add_u64 v[130:131], v[130:131], 0, v[132:133]
	v_cvt_pk_bf16_f32 v168, v122, v123
	v_cvt_pk_bf16_f32 v169, v124, v125
	v_cvt_pk_bf16_f32 v170, v126, v127
	v_cvt_pk_bf16_f32 v171, v128, v129
	v_lshl_add_u64 v[176:177], v[130:131], 0, v[180:181]
	s_nop 0
	v_permlane16_swap_b32_e32 v168, v170
	v_permlane16_swap_b32_e32 v169, v171
	global_store_dwordx4 v[176:177], v[168:171], off
	v_cvt_pk_bf16_f32 v172, v118, v119
	v_cvt_pk_bf16_f32 v173, v120, v121
	v_cvt_pk_bf16_f32 v174, v114, v115
	v_cvt_pk_bf16_f32 v175, v116, v117
	v_lshl_add_u64 v[176:177], v[130:131], 0, v[180:181]
	s_nop 0
	v_permlane16_swap_b32_e32 v172, v174
	v_permlane16_swap_b32_e32 v173, v175
	global_store_dwordx4 v[176:177], v[172:175], off offset:256
	v_or_b32_e32 v134, 16, v154
	v_ashrrev_i32_e32 v135, 31, v134
	v_lshlrev_b64 v[134:135], 13, v[134:135]
	v_lshl_add_u64 v[134:135], s[4:5], 0, v[134:135]
	v_lshl_add_u64 v[134:135], v[134:135], 0, v[132:133]
	v_cvt_pk_bf16_f32 v168, v110, v111
	v_cvt_pk_bf16_f32 v169, v112, v113
	v_cvt_pk_bf16_f32 v170, v106, v107
	v_cvt_pk_bf16_f32 v171, v108, v109
	v_lshl_add_u64 v[176:177], v[134:135], 0, v[180:181]
	s_nop 0
	v_permlane16_swap_b32_e32 v168, v170
	v_permlane16_swap_b32_e32 v169, v171
	global_store_dwordx4 v[176:177], v[168:171], off
	v_cvt_pk_bf16_f32 v172, v102, v103
	v_cvt_pk_bf16_f32 v173, v104, v105
	v_cvt_pk_bf16_f32 v174, v98, v99
	v_cvt_pk_bf16_f32 v175, v100, v101
	v_lshl_add_u64 v[176:177], v[134:135], 0, v[180:181]
	s_nop 0
	v_permlane16_swap_b32_e32 v172, v174
	v_permlane16_swap_b32_e32 v173, v175
	global_store_dwordx4 v[176:177], v[172:175], off offset:256
	v_or_b32_e32 v134, 32, v154
	v_ashrrev_i32_e32 v135, 31, v134
	v_lshlrev_b64 v[134:135], 13, v[134:135]
	v_lshl_add_u64 v[134:135], s[4:5], 0, v[134:135]
	v_lshl_add_u64 v[134:135], v[134:135], 0, v[132:133]
	v_cvt_pk_bf16_f32 v168, v94, v95
	v_cvt_pk_bf16_f32 v169, v96, v97
	v_cvt_pk_bf16_f32 v170, v90, v91
	v_cvt_pk_bf16_f32 v171, v92, v93
	v_lshl_add_u64 v[176:177], v[134:135], 0, v[180:181]
	s_nop 0
	v_permlane16_swap_b32_e32 v168, v170
	v_permlane16_swap_b32_e32 v169, v171
	global_store_dwordx4 v[176:177], v[168:171], off
	v_cvt_pk_bf16_f32 v172, v86, v87
	v_cvt_pk_bf16_f32 v173, v88, v89
	v_cvt_pk_bf16_f32 v174, v82, v83
	v_cvt_pk_bf16_f32 v175, v84, v85
	v_lshl_add_u64 v[176:177], v[134:135], 0, v[180:181]
	s_nop 0
	v_permlane16_swap_b32_e32 v172, v174
	v_permlane16_swap_b32_e32 v173, v175
	global_store_dwordx4 v[176:177], v[172:175], off offset:256
	v_or_b32_e32 v134, 48, v154
	v_ashrrev_i32_e32 v135, 31, v134
	v_lshlrev_b64 v[134:135], 13, v[134:135]
	v_lshl_add_u64 v[134:135], s[4:5], 0, v[134:135]
	v_lshl_add_u64 v[132:133], v[134:135], 0, v[132:133]
	v_cvt_pk_bf16_f32 v168, v78, v79
	v_cvt_pk_bf16_f32 v169, v80, v81
	v_cvt_pk_bf16_f32 v170, v74, v75
	v_cvt_pk_bf16_f32 v171, v76, v77
	v_lshl_add_u64 v[176:177], v[132:133], 0, v[180:181]
	s_nop 0
	v_permlane16_swap_b32_e32 v168, v170
	v_permlane16_swap_b32_e32 v169, v171
	global_store_dwordx4 v[176:177], v[168:171], off
	s_mov_b64 s[0:1], 0x100000
	v_cvt_pk_bf16_f32 v172, v70, v71
	v_cvt_pk_bf16_f32 v173, v72, v73
	v_cvt_pk_bf16_f32 v174, v66, v67
	v_cvt_pk_bf16_f32 v175, v68, v69
	v_lshl_add_u64 v[176:177], v[132:133], 0, v[180:181]
	s_nop 0
	v_permlane16_swap_b32_e32 v172, v174
	v_permlane16_swap_b32_e32 v173, v175
	global_store_dwordx4 v[176:177], v[172:175], off offset:256
	v_lshl_add_u64 v[132:133], v[130:131], 0, s[0:1]
	s_mov_b32 s0, 0x100000
	v_add_co_u32_e32 v136, vcc, s0, v130
	s_mov_b32 s0, 0x120000
	s_nop 0
	v_addc_co_u32_e32 v137, vcc, 0, v131, vcc
	v_cvt_pk_bf16_f32 v168, v62, v63
	v_cvt_pk_bf16_f32 v169, v64, v65
	v_cvt_pk_bf16_f32 v170, v58, v59
	v_cvt_pk_bf16_f32 v171, v60, v61
	v_lshl_add_u64 v[176:177], v[136:137], 0, v[180:181]
	s_nop 0
	v_permlane16_swap_b32_e32 v168, v170
	v_permlane16_swap_b32_e32 v169, v171
	global_store_dwordx4 v[176:177], v[168:171], off
	v_add_co_u32_e32 v136, vcc, s0, v130
	v_cvt_pk_bf16_f32 v172, v54, v55
	v_cvt_pk_bf16_f32 v173, v56, v57
	v_cvt_pk_bf16_f32 v174, v50, v51
	v_cvt_pk_bf16_f32 v175, v52, v53
	v_lshl_add_u64 v[176:177], v[132:133], 0, v[180:181]
	s_nop 0
	v_permlane16_swap_b32_e32 v172, v174
	v_permlane16_swap_b32_e32 v173, v175
	global_store_dwordx4 v[176:177], v[172:175], off offset:256
	s_nop 0
	v_addc_co_u32_e32 v137, vcc, 0, v131, vcc
	v_lshl_add_u64 v[132:133], v[130:131], 0, s[74:75]
	v_cvt_pk_bf16_f32 v168, v46, v47
	v_cvt_pk_bf16_f32 v169, v48, v49
	v_cvt_pk_bf16_f32 v170, v42, v43
	v_cvt_pk_bf16_f32 v171, v44, v45
	v_lshl_add_u64 v[176:177], v[136:137], 0, v[180:181]
	s_nop 0
	v_permlane16_swap_b32_e32 v168, v170
	v_permlane16_swap_b32_e32 v169, v171
	global_store_dwordx4 v[176:177], v[168:171], off
	s_mov_b64 s[0:1], 0x140000
	v_cvt_pk_bf16_f32 v172, v38, v39
	v_cvt_pk_bf16_f32 v173, v40, v41
	v_cvt_pk_bf16_f32 v174, v34, v35
	v_cvt_pk_bf16_f32 v175, v36, v37
	v_lshl_add_u64 v[176:177], v[132:133], 0, v[180:181]
	s_nop 0
	v_permlane16_swap_b32_e32 v172, v174
	v_permlane16_swap_b32_e32 v173, v175
	global_store_dwordx4 v[176:177], v[172:175], off offset:256
	v_lshl_add_u64 v[132:133], v[130:131], 0, s[0:1]
	s_mov_b32 s0, 0x140000
	v_add_co_u32_e32 v136, vcc, s0, v130
	s_mov_b64 s[0:1], 0x160000
	s_nop 0
	v_addc_co_u32_e32 v137, vcc, 0, v131, vcc
	v_cvt_pk_bf16_f32 v168, v30, v31
	v_cvt_pk_bf16_f32 v169, v32, v33
	v_cvt_pk_bf16_f32 v170, v26, v27
	v_cvt_pk_bf16_f32 v171, v28, v29
	v_lshl_add_u64 v[176:177], v[136:137], 0, v[180:181]
	s_nop 0
	v_permlane16_swap_b32_e32 v168, v170
	v_permlane16_swap_b32_e32 v169, v171
	global_store_dwordx4 v[176:177], v[168:171], off
	v_cvt_pk_bf16_f32 v172, v22, v23
	v_cvt_pk_bf16_f32 v173, v24, v25
	v_cvt_pk_bf16_f32 v174, v18, v19
	v_cvt_pk_bf16_f32 v175, v20, v21
	v_lshl_add_u64 v[176:177], v[132:133], 0, v[180:181]
	s_nop 0
	v_permlane16_swap_b32_e32 v172, v174
	v_permlane16_swap_b32_e32 v173, v175
	global_store_dwordx4 v[176:177], v[172:175], off offset:256
	v_lshl_add_u64 v[132:133], v[130:131], 0, s[0:1]
	s_mov_b32 s0, 0x160000
	v_add_co_u32_e32 v130, vcc, s0, v130
	s_mov_b64 s[0:1], 0
	s_nop 0
	v_addc_co_u32_e32 v131, vcc, 0, v131, vcc
	v_cvt_pk_bf16_f32 v168, v14, v15
	v_cvt_pk_bf16_f32 v169, v16, v17
	v_cvt_pk_bf16_f32 v170, v10, v11
	v_cvt_pk_bf16_f32 v171, v12, v13
	v_lshl_add_u64 v[176:177], v[130:131], 0, v[180:181]
	s_nop 0
	v_permlane16_swap_b32_e32 v168, v170
	v_permlane16_swap_b32_e32 v169, v171
	global_store_dwordx4 v[176:177], v[168:171], off
	v_cvt_pk_bf16_f32 v172, v6, v7
	v_cvt_pk_bf16_f32 v173, v8, v9
	v_cvt_pk_bf16_f32 v174, v2, v3
	v_cvt_pk_bf16_f32 v175, v4, v5
	v_lshl_add_u64 v[176:177], v[132:133], 0, v[180:181]
	s_nop 0
	v_permlane16_swap_b32_e32 v172, v174
	v_permlane16_swap_b32_e32 v173, v175
	global_store_dwordx4 v[176:177], v[172:175], off offset:256

; __device__ __forceinline__ unsigned ld_agent(const unsigned* p) { return __hip_atomic_load(p, __ATOMIC_RELAXED, __HIP_MEMORY_SCOPE_AGENT); }
;     __device__ __forceinline__ void fused(f32x4 (&acc)[2][2][4][2], const Unit& u, int wr, int wc, int fr, int fq, LAS unsigned char* lds, int tid, KP p, int code) const {
;     ...
;         if (tid < 256) {
;             float s = 0.f;
; #pragma unroll
;             for (int k = 0; k < 8; ++k) s += __uint_as_float(ld_agent(X + tid * 8 + k));
;             const float rs = 1.0f / sqrtf(s * (1.0f / DM) + 1e-6f);
;             S[tid] = rs;
;             if (nmode == 1 && u.pn == 0) ((float*)(ws + WS_RSTD))[u.pm * BM + tid] = rs;
;         }
.LBB0_406:
	s_or_b64 exec, exec, s[22:23]
	s_barrier
	s_and_saveexec_b64 s[22:23], s[4:5]
	s_cbranch_execz .LBB0_409
	v_lshl_add_u64 v[186:187], v[186:187], 2, s[24:25]
	global_load_dwordx4 v[164:167], v[186:187], off sc1
	global_load_dwordx4 v[168:171], v[186:187], off offset:16 sc1
	s_cmp_lg_u32 s16, 0
	s_waitcnt vmcnt(0)
	v_add_f32_e32 v182, 0, v164
	v_add_f32_e32 v182, v182, v165
	v_add_f32_e32 v182, v182, v166
	v_add_f32_e32 v182, v182, v167
	v_add_f32_e32 v182, v182, v168
	v_add_f32_e32 v182, v182, v169
	v_add_f32_e32 v182, v182, v170
	v_add_f32_e32 v182, v182, v171
	v_fmamk_f32 v182, v182, 0x3a000000, v217
	v_cmp_gt_f32_e32 vcc, s40, v182
	v_mul_f32_e32 v186, 0x4f800000, v182
	s_nop 0
	v_cndmask_b32_e32 v182, v182, v186, vcc
	v_sqrt_f32_e32 v186, v182
	s_nop 0
	v_add_u32_e32 v187, -1, v186
	v_fma_f32 v188, -v187, v186, v182
	v_cmp_ge_f32_e64 s[4:5], 0, v188
	v_add_u32_e32 v188, 1, v186
	s_nop 0
	v_cndmask_b32_e64 v187, v186, v187, s[4:5]
	v_fma_f32 v186, -v188, v186, v182
	v_cmp_lt_f32_e64 s[4:5], 0, v186
	s_nop 1
	v_cndmask_b32_e64 v186, v187, v188, s[4:5]
	v_mul_f32_e32 v187, 0x37800000, v186
	v_cndmask_b32_e32 v186, v186, v187, vcc
	v_cmp_class_f32_e32 vcc, v182, v216
	s_nop 1
	v_cndmask_b32_e32 v182, v186, v182, vcc
	v_div_scale_f32 v186, s[0:1], v182, v182, 1.0
	v_rcp_f32_e32 v187, v186
	s_cselect_b64 s[0:1], -1, 0
	s_xor_b64 s[4:5], s[20:21], -1
	s_or_b64 s[0:1], s[4:5], s[0:1]
	v_fma_f32 v188, -v186, v187, 1.0
	v_fmac_f32_e32 v187, v188, v187
	v_div_scale_f32 v188, vcc, 1.0, v182, 1.0
	v_mul_f32_e32 v189, v188, v187
	v_fma_f32 v190, -v186, v189, v188
	v_fmac_f32_e32 v189, v190, v187
	v_fma_f32 v186, -v186, v189, v188
	v_div_fmas_f32 v186, v186, v187, v189
	v_div_fixup_f32 v182, v186, v182, 1.0
	v_lshl_add_u32 v186, v163, 2, 0
	s_and_b64 vcc, exec, s[0:1]
	ds_write_b32 v186, v182 offset:4096
	s_cbranch_vccnz .LBB0_409
	v_add_u32_e32 v186, s10, v163
	v_ashrrev_i32_e32 v187, 31, v186
	v_lshl_add_u64 v[186:187], v[186:187], 2, s[14:15]
	v_add_co_u32_e32 v186, vcc, 0x30ab4000, v186
	s_nop 1
	v_addc_co_u32_e32 v187, vcc, 0, v187, vcc
	global_store_dword v[186:187], v182, off

; #define PG8_STAGE(bufoff, gbase, voff) do { _Pragma("unroll") for (int _i = 0; _i < 2; ++_i) \
;         __builtin_amdgcn_global_load_lds((const unsigned*)((const char*)(gbase) + (voff)[_i]), (LAS unsigned*)(lds + (bufoff) + ldsw + _i * 8192), 16, 0, 0); } while (0)
; #define PG8_LDA(dst, b, h) do { _Pragma("unroll") for (int m = 0; m < 4; ++m) _Pragma("unroll") for (int k = 0; k < 2; ++k) dst[m][k] = *(const LAS bf16x8*)(lds + PG8_SA(b, h) + aoff + m * 2048 + k * 1024); } while (0)
; #define PG8_LDB(dst, b, h) do { _Pragma("unroll") for (int n = 0; n < 2; ++n) _Pragma("unroll") for (int k = 0; k < 2; ++k) dst[n][k] = *(const LAS bf16x8*)(lds + PG8_SB(b, h) + boff + n * 2048 + k * 1024); } while (0)
; #define PG8_MMA(ai, bj, At, Bt) do { __builtin_amdgcn_s_setprio(1); _Pragma("unroll") for (int m = 0; m < 4; ++m) _Pragma("unroll") for (int n = 0; n < 2; ++n) _Pragma("unroll") for (int k = 0; k < 2; ++k) \
;         acc[ai][bj][m][n] = __builtin_amdgcn_mfma_f32_16x16x32_bf16(Bt[n][k], At[m][k], acc[ai][bj][m][n], 0, 0, 0); __builtin_amdgcn_s_setprio(0); } while (0)
; #define PG8_WAIT_V(n) asm volatile("s_waitcnt vmcnt(" #n ")" ::: "memory")
; #define PG8_WAIT_L(n) asm volatile("s_waitcnt lgkmcnt(" #n ")" ::: "memory")
; #define PG8_BAR __builtin_amdgcn_s_barrier()
; #define PG8_SCHED __builtin_amdgcn_sched_barrier(0)
; template <class Epi>
; __device__ __forceinline__ void gemm_phase(LAS unsigned char* lds, const Gemm g, const Order& S, KP kp, int code, int wv) {
;     ...
;             PG8_LDB(B0, 0, 0); PG8_SCHED; PG8_LDA(At, 0, 0); PG8_STAGE(PG8_SA(1, 1), a1 + hstepA, voffA);
;             PG8_WAIT_L(8); PG8_BAR; PG8_WAIT_L(0); PG8_MMA(0, 0, At, B0); PG8_BAR; PG8_SCHED;
;             PG8_LDB(B1, 0, 1); PG8_STAGE(PG8_SB(0, 0), b2, voffB);
;             PG8_BAR; PG8_WAIT_L(0); PG8_MMA(0, 1, At, B1); PG8_BAR;
;             PG8_LDA(At, 0, 1); PG8_STAGE(PG8_SA(0, 0), a2, voffA);
;             PG8_BAR; PG8_WAIT_L(0); PG8_MMA(1, 0, At, B0); PG8_BAR; PG8_SCHED;
;             PG8_STAGE(PG8_SB(0, 1), b2 + hstepB, voffB);
;             PG8_WAIT_V(6); PG8_BAR; PG8_MMA(1, 1, At, B1); PG8_BAR;
;             PG8_LDB(B0, 1, 0); PG8_SCHED; PG8_LDA(At, 1, 0); PG8_STAGE(PG8_SA(0, 1), a2 + hstepA, voffA);
;             PG8_WAIT_L(8); PG8_BAR; PG8_WAIT_L(0); PG8_MMA(0, 0, At, B0); PG8_BAR; PG8_SCHED;
.LBB0_550:
	s_add_u32 s18, s16, 0xfff80080
	s_addc_u32 s19, s17, -1
	s_add_i32 s38, 0, 0x10000
	v_add_u32_e32 v156, s38, v145
	ds_read_b128 v[140:143], v156
	ds_read_b128 v[148:151], v156 offset:1024
	ds_read_b128 v[152:155], v156 offset:2048
	ds_read_b128 v[156:159], v156 offset:3072
	s_cmp_eq_u32 s37, 28
	s_cselect_b32 s21, s0, s19
	s_cselect_b32 s20, s1, s18
	s_cselect_b32 s19, s5, s36
	s_cselect_b32 s18, s7, s11
	v_lshl_add_u64 v[160:161], s[16:17], 0, v[136:137]
	s_add_i32 m0, s15, 0xc000
	ds_read_b128 v[184:187], v147
	ds_read_b128 v[188:191], v147 offset:1024
	ds_read_b128 v[192:195], v147 offset:2048
	ds_read_b128 v[196:199], v147 offset:3072
	ds_read_b128 v[200:203], v147 offset:4096
	ds_read_b128 v[204:207], v147 offset:5120
	ds_read_b128 v[208:211], v147 offset:6144
	ds_read_b128 v[224:227], v147 offset:7168
	global_load_lds_dwordx4 v[160:161], off
	v_lshl_add_u64 v[160:161], s[16:17], 0, v[138:139]
	s_add_i32 m0, s15, 0xe000
	s_nop 0
	global_load_lds_dwordx4 v[160:161], off
	s_waitcnt lgkmcnt(8)
	s_barrier
	s_waitcnt lgkmcnt(0)
	s_setprio 1
	s_waitcnt lgkmcnt(0)
	v_mfma_f32_16x16x32_bf16 v[126:129], v[140:143], v[184:187], v[126:129]
	v_mfma_f32_16x16x32_bf16 v[118:121], v[152:155], v[184:187], v[118:121]
	v_mfma_f32_16x16x32_bf16 v[110:113], v[140:143], v[192:195], v[110:113]
	v_mfma_f32_16x16x32_bf16 v[102:105], v[152:155], v[192:195], v[102:105]
	v_mfma_f32_16x16x32_bf16 v[94:97], v[140:143], v[200:203], v[94:97]
	v_mfma_f32_16x16x32_bf16 v[86:89], v[152:155], v[200:203], v[86:89]
	v_mfma_f32_16x16x32_bf16 v[78:81], v[140:143], v[208:211], v[78:81]
	v_mfma_f32_16x16x32_bf16 v[70:73], v[152:155], v[208:211], v[70:73]
	v_mfma_f32_16x16x32_bf16 v[126:129], v[148:151], v[188:191], v[126:129]
	v_mfma_f32_16x16x32_bf16 v[118:121], v[156:159], v[188:191], v[118:121]
	v_mfma_f32_16x16x32_bf16 v[110:113], v[148:151], v[196:199], v[110:113]
	v_mfma_f32_16x16x32_bf16 v[102:105], v[156:159], v[196:199], v[102:105]
	v_mfma_f32_16x16x32_bf16 v[94:97], v[148:151], v[204:207], v[94:97]
	v_mfma_f32_16x16x32_bf16 v[86:89], v[156:159], v[204:207], v[86:89]
	v_mfma_f32_16x16x32_bf16 v[78:81], v[148:151], v[224:227], v[78:81]
	v_mfma_f32_16x16x32_bf16 v[70:73], v[156:159], v[224:227], v[70:73]
	s_setprio 0
	s_barrier
	s_add_i32 s40, 0, 0x14000
	v_add_u32_e32 v160, s40, v145
	s_add_i32 s38, s38, s24
	ds_read_b128 v[228:231], v160
	ds_read_b128 v[232:235], v160 offset:1024
	ds_read_b128 v[236:239], v160 offset:2048
	ds_read_b128 v[240:243], v160 offset:3072
	v_lshl_add_u64 v[160:161], s[18:19], 0, v[0:1]
	s_mov_b32 m0, s38
	v_lshl_add_u64 v[212:213], s[18:19], 0, v[130:131]
	global_load_lds_dwordx4 v[160:161], off
	s_add_i32 m0, s38, 0x2000
	s_nop 0
	global_load_lds_dwordx4 v[212:213], off
	s_barrier
	s_waitcnt lgkmcnt(0)
	s_setprio 1
	s_waitcnt lgkmcnt(0)
	v_mfma_f32_16x16x32_bf16 v[122:125], v[228:231], v[184:187], v[122:125]
	v_mfma_f32_16x16x32_bf16 v[114:117], v[236:239], v[184:187], v[114:117]
	v_mfma_f32_16x16x32_bf16 v[106:109], v[228:231], v[192:195], v[106:109]
	v_mfma_f32_16x16x32_bf16 v[98:101], v[236:239], v[192:195], v[98:101]
	v_mfma_f32_16x16x32_bf16 v[90:93], v[228:231], v[200:203], v[90:93]
	v_mfma_f32_16x16x32_bf16 v[82:85], v[236:239], v[200:203], v[82:85]
	v_mfma_f32_16x16x32_bf16 v[74:77], v[228:231], v[208:211], v[74:77]
	v_mfma_f32_16x16x32_bf16 v[66:69], v[236:239], v[208:211], v[66:69]
	v_mfma_f32_16x16x32_bf16 v[122:125], v[232:235], v[188:191], v[122:125]
	v_mfma_f32_16x16x32_bf16 v[114:117], v[240:243], v[188:191], v[114:117]
	v_mfma_f32_16x16x32_bf16 v[106:109], v[232:235], v[196:199], v[106:109]
	v_mfma_f32_16x16x32_bf16 v[98:101], v[240:243], v[196:199], v[98:101]
	v_mfma_f32_16x16x32_bf16 v[90:93], v[232:235], v[204:207], v[90:93]
	v_mfma_f32_16x16x32_bf16 v[82:85], v[240:243], v[204:207], v[82:85]
	v_mfma_f32_16x16x32_bf16 v[74:77], v[232:235], v[224:227], v[74:77]
	v_mfma_f32_16x16x32_bf16 v[66:69], v[240:243], v[224:227], v[66:69]
	s_setprio 0
	s_mov_b32 m0, s15
	v_lshl_add_u64 v[218:219], s[20:21], 0, v[134:135]
	s_barrier
	ds_read_b128 v[184:187], v147 offset:16384
	ds_read_b128 v[188:191], v147 offset:17408
	ds_read_b128 v[192:195], v147 offset:18432
	ds_read_b128 v[196:199], v147 offset:19456
	ds_read_b128 v[200:203], v147 offset:20480
	ds_read_b128 v[204:207], v147 offset:21504
	ds_read_b128 v[208:211], v147 offset:22528
	ds_read_b128 v[224:227], v147 offset:23552
	global_load_lds_dwordx4 v[218:219], off
	v_lshl_add_u64 v[244:245], s[20:21], 0, v[132:133]
	s_mov_b32 m0, s28
	s_nop 0
	global_load_lds_dwordx4 v[244:245], off
	s_barrier
	s_waitcnt lgkmcnt(0)
	s_setprio 1
	s_waitcnt lgkmcnt(0)
	v_mfma_f32_16x16x32_bf16 v[62:65], v[140:143], v[184:187], v[62:65]
	v_mfma_f32_16x16x32_bf16 v[54:57], v[152:155], v[184:187], v[54:57]
	v_mfma_f32_16x16x32_bf16 v[46:49], v[140:143], v[192:195], v[46:49]
	v_mfma_f32_16x16x32_bf16 v[38:41], v[152:155], v[192:195], v[38:41]
	v_mfma_f32_16x16x32_bf16 v[30:33], v[140:143], v[200:203], v[30:33]
	v_mfma_f32_16x16x32_bf16 v[22:25], v[152:155], v[200:203], v[22:25]
	v_mfma_f32_16x16x32_bf16 v[14:17], v[140:143], v[208:211], v[14:17]
	v_mfma_f32_16x16x32_bf16 v[6:9], v[152:155], v[208:211], v[6:9]
	v_mfma_f32_16x16x32_bf16 v[62:65], v[148:151], v[188:191], v[62:65]
	v_mfma_f32_16x16x32_bf16 v[54:57], v[156:159], v[188:191], v[54:57]
	v_mfma_f32_16x16x32_bf16 v[46:49], v[148:151], v[196:199], v[46:49]
	v_mfma_f32_16x16x32_bf16 v[38:41], v[156:159], v[196:199], v[38:41]
	v_mfma_f32_16x16x32_bf16 v[30:33], v[148:151], v[204:207], v[30:33]
	v_mfma_f32_16x16x32_bf16 v[22:25], v[156:159], v[204:207], v[22:25]
	v_mfma_f32_16x16x32_bf16 v[14:17], v[148:151], v[224:227], v[14:17]
	v_mfma_f32_16x16x32_bf16 v[6:9], v[156:159], v[224:227], v[6:9]
	s_setprio 0
	s_barrier
; #define PG8_STAGE(bufoff, gbase, voff) do { _Pragma("unroll") for (int _i = 0; _i < 2; ++_i) \
;         __builtin_amdgcn_global_load_lds((const unsigned*)((const char*)(gbase) + (voff)[_i]), (LAS unsigned*)(lds + (bufoff) + ldsw + _i * 8192), 16, 0, 0); } while (0)
; #define PG8_LDA(dst, b, h) do { _Pragma("unroll") for (int m = 0; m < 4; ++m) _Pragma("unroll") for (int k = 0; k < 2; ++k) dst[m][k] = *(const LAS bf16x8*)(lds + PG8_SA(b, h) + aoff + m * 2048 + k * 1024); } while (0)
; #define PG8_LDB(dst, b, h) do { _Pragma("unroll") for (int n = 0; n < 2; ++n) _Pragma("unroll") for (int k = 0; k < 2; ++k) dst[n][k] = *(const LAS bf16x8*)(lds + PG8_SB(b, h) + boff + n * 2048 + k * 1024); } while (0)
; #define PG8_MMA(ai, bj, At, Bt) do { __builtin_amdgcn_s_setprio(1); _Pragma("unroll") for (int m = 0; m < 4; ++m) _Pragma("unroll") for (int n = 0; n < 2; ++n) _Pragma("unroll") for (int k = 0; k < 2; ++k) \
;         acc[ai][bj][m][n] = __builtin_amdgcn_mfma_f32_16x16x32_bf16(Bt[n][k], At[m][k], acc[ai][bj][m][n], 0, 0, 0); __builtin_amdgcn_s_setprio(0); } while (0)
; #define PG8_WAIT_V(n) asm volatile("s_waitcnt vmcnt(" #n ")" ::: "memory")
; #define PG8_WAIT_L(n) asm volatile("s_waitcnt lgkmcnt(" #n ")" ::: "memory")
; #define PG8_BAR __builtin_amdgcn_s_barrier()
; #define PG8_SCHED __builtin_amdgcn_sched_barrier(0)
; template <class Epi>
; __device__ __forceinline__ void gemm_phase(LAS unsigned char* lds, const Gemm g, const Order& S, KP kp, int code, int wv) {
;     ...
;             PG8_STAGE(PG8_SB(0, 1), b2 + hstepB, voffB);
;             PG8_WAIT_V(6); PG8_BAR; PG8_MMA(1, 1, At, B1); PG8_BAR;
;             PG8_LDB(B0, 1, 0); PG8_SCHED; PG8_LDA(At, 1, 0); PG8_STAGE(PG8_SA(0, 1), a2 + hstepA, voffA);
;             PG8_WAIT_L(8); PG8_BAR; PG8_WAIT_L(0); PG8_MMA(0, 0, At, B0); PG8_BAR; PG8_SCHED;
;             PG8_LDB(B1, 1, 1); PG8_STAGE(PG8_SB(1, 0), b3, voffB);
;             PG8_BAR; PG8_WAIT_L(0); PG8_MMA(0, 1, At, B1); PG8_BAR;
;             PG8_LDA(At, 1, 1); PG8_STAGE(PG8_SA(1, 0), a3, voffA);
;             PG8_BAR; PG8_WAIT_L(0); PG8_MMA(1, 0, At, B0); PG8_BAR; PG8_SCHED;
;             PG8_STAGE(PG8_SB(1, 1), b3 + hstepB, voffB);
;             PG8_WAIT_V(6); PG8_BAR; PG8_MMA(1, 1, At, B1); PG8_BAR;
	s_add_u32 s38, s18, 0x80000
	s_addc_u32 s39, s19, 0
	s_add_i32 s40, s40, s24
	v_lshl_add_u64 v[140:141], s[38:39], 0, v[0:1]
	s_mov_b32 m0, s40
	s_nop 0
	global_load_lds_dwordx4 v[140:141], off
	v_lshl_add_u64 v[140:141], s[38:39], 0, v[130:131]
	s_add_i32 m0, s40, 0x2000
	s_nop 0
	global_load_lds_dwordx4 v[140:141], off
	s_waitcnt vmcnt(6)
	s_barrier
	s_setprio 1
	v_mfma_f32_16x16x32_bf16 v[58:61], v[228:231], v[184:187], v[58:61]
	v_mfma_f32_16x16x32_bf16 v[50:53], v[236:239], v[184:187], v[50:53]
	v_mfma_f32_16x16x32_bf16 v[42:45], v[228:231], v[192:195], v[42:45]
	v_mfma_f32_16x16x32_bf16 v[34:37], v[236:239], v[192:195], v[34:37]
	v_mfma_f32_16x16x32_bf16 v[26:29], v[228:231], v[200:203], v[26:29]
	v_mfma_f32_16x16x32_bf16 v[18:21], v[236:239], v[200:203], v[18:21]
	v_mfma_f32_16x16x32_bf16 v[10:13], v[228:231], v[208:211], v[10:13]
	v_mfma_f32_16x16x32_bf16 v[2:5], v[236:239], v[208:211], v[2:5]
	v_mfma_f32_16x16x32_bf16 v[58:61], v[232:235], v[188:191], v[58:61]
	v_mfma_f32_16x16x32_bf16 v[50:53], v[240:243], v[188:191], v[50:53]
	v_mfma_f32_16x16x32_bf16 v[42:45], v[232:235], v[196:199], v[42:45]
	v_mfma_f32_16x16x32_bf16 v[34:37], v[240:243], v[196:199], v[34:37]
	v_mfma_f32_16x16x32_bf16 v[26:29], v[232:235], v[204:207], v[26:29]
	v_mfma_f32_16x16x32_bf16 v[18:21], v[240:243], v[204:207], v[18:21]
	v_mfma_f32_16x16x32_bf16 v[10:13], v[232:235], v[224:227], v[10:13]
	v_mfma_f32_16x16x32_bf16 v[2:5], v[240:243], v[224:227], v[2:5]
	s_setprio 0
	s_add_i32 s38, 0, 0x18000
	v_add_u32_e32 v156, s38, v145
	s_barrier
	ds_read_b128 v[140:143], v156
	ds_read_b128 v[148:151], v156 offset:1024
	ds_read_b128 v[152:155], v156 offset:2048
	ds_read_b128 v[156:159], v156 offset:3072
	s_add_u32 s20, s20, 0x80000
	s_addc_u32 s21, s21, 0
	s_mov_b32 m0, s29
	v_lshl_add_u64 v[228:229], s[20:21], 0, v[134:135]
	ds_read_b128 v[184:187], v147 offset:32768
	ds_read_b128 v[188:191], v147 offset:33792
	ds_read_b128 v[192:195], v147 offset:34816
	ds_read_b128 v[196:199], v147 offset:35840
	ds_read_b128 v[200:203], v147 offset:36864
	ds_read_b128 v[204:207], v147 offset:37888
	ds_read_b128 v[208:211], v147 offset:38912
	ds_read_b128 v[224:227], v147 offset:39936
	global_load_lds_dwordx4 v[228:229], off
	v_lshl_add_u64 v[228:229], s[20:21], 0, v[132:133]
	s_mov_b32 m0, s30
	s_nop 0
	global_load_lds_dwordx4 v[228:229], off
	s_waitcnt lgkmcnt(8)
	s_barrier
	s_waitcnt lgkmcnt(0)
	s_setprio 1
	s_waitcnt lgkmcnt(0)
	v_mfma_f32_16x16x32_bf16 v[126:129], v[140:143], v[184:187], v[126:129]
	v_mfma_f32_16x16x32_bf16 v[118:121], v[152:155], v[184:187], v[118:121]
	v_mfma_f32_16x16x32_bf16 v[110:113], v[140:143], v[192:195], v[110:113]
	v_mfma_f32_16x16x32_bf16 v[102:105], v[152:155], v[192:195], v[102:105]
	v_mfma_f32_16x16x32_bf16 v[94:97], v[140:143], v[200:203], v[94:97]
	v_mfma_f32_16x16x32_bf16 v[86:89], v[152:155], v[200:203], v[86:89]
	v_mfma_f32_16x16x32_bf16 v[78:81], v[140:143], v[208:211], v[78:81]
	v_mfma_f32_16x16x32_bf16 v[70:73], v[152:155], v[208:211], v[70:73]
	v_mfma_f32_16x16x32_bf16 v[126:129], v[148:151], v[188:191], v[126:129]
	v_mfma_f32_16x16x32_bf16 v[118:121], v[156:159], v[188:191], v[118:121]
	v_mfma_f32_16x16x32_bf16 v[110:113], v[148:151], v[196:199], v[110:113]
	v_mfma_f32_16x16x32_bf16 v[102:105], v[156:159], v[196:199], v[102:105]
	v_mfma_f32_16x16x32_bf16 v[94:97], v[148:151], v[204:207], v[94:97]
	v_mfma_f32_16x16x32_bf16 v[86:89], v[156:159], v[204:207], v[86:89]
	v_mfma_f32_16x16x32_bf16 v[78:81], v[148:151], v[224:227], v[78:81]
	v_mfma_f32_16x16x32_bf16 v[70:73], v[156:159], v[224:227], v[70:73]
	s_setprio 0
	s_barrier
	s_add_i32 s20, 0, 0x1c000
	s_add_i32 s21, s38, s24
	v_add_u32_e32 v163, s20, v145
	v_lshl_add_u64 v[160:161], v[160:161], 0, s[70:71]
	s_mov_b32 m0, s21
	ds_read_b128 v[228:231], v163
	ds_read_b128 v[232:235], v163 offset:1024
	ds_read_b128 v[236:239], v163 offset:2048
	ds_read_b128 v[240:243], v163 offset:3072
	global_load_lds_dwordx4 v[160:161], off
	v_lshl_add_u64 v[160:161], v[212:213], 0, s[70:71]
	s_add_i32 m0, s21, 0x2000
	s_nop 0
	global_load_lds_dwordx4 v[160:161], off
	s_barrier
	s_waitcnt lgkmcnt(0)
	s_setprio 1
	s_waitcnt lgkmcnt(0)
	v_mfma_f32_16x16x32_bf16 v[122:125], v[228:231], v[184:187], v[122:125]
	v_mfma_f32_16x16x32_bf16 v[114:117], v[236:239], v[184:187], v[114:117]
	v_mfma_f32_16x16x32_bf16 v[106:109], v[228:231], v[192:195], v[106:109]
	v_mfma_f32_16x16x32_bf16 v[98:101], v[236:239], v[192:195], v[98:101]
	v_mfma_f32_16x16x32_bf16 v[90:93], v[228:231], v[200:203], v[90:93]
	v_mfma_f32_16x16x32_bf16 v[82:85], v[236:239], v[200:203], v[82:85]
	v_mfma_f32_16x16x32_bf16 v[74:77], v[228:231], v[208:211], v[74:77]
	v_mfma_f32_16x16x32_bf16 v[66:69], v[236:239], v[208:211], v[66:69]
	v_mfma_f32_16x16x32_bf16 v[122:125], v[232:235], v[188:191], v[122:125]
	v_mfma_f32_16x16x32_bf16 v[114:117], v[240:243], v[188:191], v[114:117]
	v_mfma_f32_16x16x32_bf16 v[106:109], v[232:235], v[196:199], v[106:109]
	v_mfma_f32_16x16x32_bf16 v[98:101], v[240:243], v[196:199], v[98:101]
	v_mfma_f32_16x16x32_bf16 v[90:93], v[232:235], v[204:207], v[90:93]
	v_mfma_f32_16x16x32_bf16 v[82:85], v[240:243], v[204:207], v[82:85]
	v_mfma_f32_16x16x32_bf16 v[74:77], v[232:235], v[224:227], v[74:77]
	v_mfma_f32_16x16x32_bf16 v[66:69], v[240:243], v[224:227], v[66:69]
	s_setprio 0
	s_mov_b32 m0, s31
	v_lshl_add_u64 v[160:161], v[218:219], 0, s[70:71]
	s_barrier
	ds_read_b128 v[184:187], v147 offset:49152
	ds_read_b128 v[188:191], v147 offset:50176
	ds_read_b128 v[192:195], v147 offset:51200
	ds_read_b128 v[196:199], v147 offset:52224
	ds_read_b128 v[200:203], v147 offset:53248
	ds_read_b128 v[204:207], v147 offset:54272
	ds_read_b128 v[208:211], v147 offset:55296
	ds_read_b128 v[224:227], v147 offset:56320
	global_load_lds_dwordx4 v[160:161], off
	v_lshl_add_u64 v[160:161], v[244:245], 0, s[70:71]
	s_mov_b32 m0, s34
	s_nop 0
	global_load_lds_dwordx4 v[160:161], off
	s_barrier
; __device__ __forceinline__ unsigned cvt_pk_bf16(float lo, float hi) { unsigned r; asm("v_cvt_pk_bf16_f32 %0, %1, %2" : "=v"(r) : "v"(lo), "v"(hi)); return r; }
; __device__ __forceinline__ float silu_fast(float x) { return x * __builtin_amdgcn_rcpf(1.0f + __expf(-x)); }
; #define PG8_STAGE(bufoff, gbase, voff) do { _Pragma("unroll") for (int _i = 0; _i < 2; ++_i) \
;         __builtin_amdgcn_global_load_lds((const unsigned*)((const char*)(gbase) + (voff)[_i]), (LAS unsigned*)(lds + (bufoff) + ldsw + _i * 8192), 16, 0, 0); } while (0)
; #define PG8_WAIT_V(n) asm volatile("s_waitcnt vmcnt(" #n ")" ::: "memory")
; #define PG8_WAIT_L(n) asm volatile("s_waitcnt lgkmcnt(" #n ")" ::: "memory")
; #define PG8_BAR __builtin_amdgcn_s_barrier()
; #define PG8_SCHED __builtin_amdgcn_sched_barrier(0)
;     __device__ __forceinline__ void operator()(const f32x4 (&acc)[2][2][4][2], const Unit& u, int wr, int wc, int fr, int fq) const {
;         const int row0 = u.pm * BM + wr * 64 + fr, col0 = u.pn * 128 + wc * 32 + 8 * fq;
; #pragma unroll
;         for (int ai = 0; ai < 2; ++ai)
; #pragma unroll
;             for (int m = 0; m < 4; ++m) {
;                 bf16_t* rowp = O + (size_t)(row0 + ai * HALF + m * 16) * DFF + col0;
;                 const f32x4 g0 = acc[ai][0][m][0], g1 = acc[ai][0][m][1], u0 = acc[ai][1][m][0], u1 = acc[ai][1][m][1];
;                 u32x4 w;
;                 w.x = cvt_pk_bf16(silu_fast(g0[0]) * u0[0], silu_fast(g0[1]) * u0[1]);
;                 w.y = cvt_pk_bf16(silu_fast(g0[2]) * u0[2], silu_fast(g0[3]) * u0[3]);
;                 w.z = cvt_pk_bf16(silu_fast(g1[0]) * u1[0], silu_fast(g1[1]) * u1[1]);
;                 w.w = cvt_pk_bf16(silu_fast(g1[2]) * u1[2], silu_fast(g1[3]) * u1[3]);
;                 *(u32x4*)rowp = w;
;             }
;     }
; template <class Epi>
; __device__ __forceinline__ void gemm_phase(LAS unsigned char* lds, const Gemm g, const Order& S, KP kp, int code, int wv) {
;     ...
;             PG8_BAR; PG8_WAIT_L(0); PG8_MMA(1, 0, At, B0); PG8_BAR; PG8_SCHED;
;             PG8_STAGE(PG8_SB(1, 1), b3 + hstepB, voffB);
;             PG8_WAIT_V(6); PG8_BAR; PG8_MMA(1, 1, At, B1); PG8_BAR;
;         }
;         if (!Epi::HAS_FUSED || (code & 8)) { KP kq = kp; asm volatile("" : "+s"(kq)); const Epi E = Epi::make(kq, code); E(acc, cur, wr, wc, fr, fq); }
	s_waitcnt lgkmcnt(0)
	s_setprio 1
	s_waitcnt lgkmcnt(0)
	v_mfma_f32_16x16x32_bf16 v[62:65], v[140:143], v[184:187], v[62:65]
	v_mfma_f32_16x16x32_bf16 v[54:57], v[152:155], v[184:187], v[54:57]
	v_mfma_f32_16x16x32_bf16 v[46:49], v[140:143], v[192:195], v[46:49]
	v_mfma_f32_16x16x32_bf16 v[38:41], v[152:155], v[192:195], v[38:41]
	v_mfma_f32_16x16x32_bf16 v[30:33], v[140:143], v[200:203], v[30:33]
	v_mfma_f32_16x16x32_bf16 v[22:25], v[152:155], v[200:203], v[22:25]
	v_mfma_f32_16x16x32_bf16 v[14:17], v[140:143], v[208:211], v[14:17]
	v_mfma_f32_16x16x32_bf16 v[6:9], v[152:155], v[208:211], v[6:9]
	v_mfma_f32_16x16x32_bf16 v[62:65], v[148:151], v[188:191], v[62:65]
	v_mfma_f32_16x16x32_bf16 v[54:57], v[156:159], v[188:191], v[54:57]
	v_mfma_f32_16x16x32_bf16 v[46:49], v[148:151], v[196:199], v[46:49]
	v_mfma_f32_16x16x32_bf16 v[38:41], v[156:159], v[196:199], v[38:41]
	v_mfma_f32_16x16x32_bf16 v[30:33], v[148:151], v[204:207], v[30:33]
	v_mfma_f32_16x16x32_bf16 v[22:25], v[156:159], v[204:207], v[22:25]
	v_mfma_f32_16x16x32_bf16 v[14:17], v[148:151], v[224:227], v[14:17]
	v_mfma_f32_16x16x32_bf16 v[6:9], v[156:159], v[224:227], v[6:9]
	s_setprio 0
	s_barrier
	s_add_u32 s18, s18, 0x80080
	s_addc_u32 s19, s19, 0
	s_add_i32 s20, s20, s24
	v_lshl_add_u64 v[140:141], s[18:19], 0, v[0:1]
	s_mov_b32 m0, s20
	s_nop 0
	global_load_lds_dwordx4 v[140:141], off
	v_lshl_add_u64 v[140:141], s[18:19], 0, v[130:131]
	s_add_i32 m0, s20, 0x2000
	s_nop 0
	global_load_lds_dwordx4 v[140:141], off
	s_waitcnt vmcnt(6)
	s_barrier
	s_setprio 1
	v_mfma_f32_16x16x32_bf16 v[58:61], v[228:231], v[184:187], v[58:61]
	v_mfma_f32_16x16x32_bf16 v[50:53], v[236:239], v[184:187], v[50:53]
	v_mfma_f32_16x16x32_bf16 v[42:45], v[228:231], v[192:195], v[42:45]
	v_mfma_f32_16x16x32_bf16 v[34:37], v[236:239], v[192:195], v[34:37]
	v_mfma_f32_16x16x32_bf16 v[26:29], v[228:231], v[200:203], v[26:29]
	v_mfma_f32_16x16x32_bf16 v[18:21], v[236:239], v[200:203], v[18:21]
	v_mfma_f32_16x16x32_bf16 v[10:13], v[228:231], v[208:211], v[10:13]
	v_mfma_f32_16x16x32_bf16 v[2:5], v[236:239], v[208:211], v[2:5]
	v_mfma_f32_16x16x32_bf16 v[58:61], v[232:235], v[188:191], v[58:61]
	v_mfma_f32_16x16x32_bf16 v[50:53], v[240:243], v[188:191], v[50:53]
	v_mfma_f32_16x16x32_bf16 v[42:45], v[232:235], v[196:199], v[42:45]
	v_mfma_f32_16x16x32_bf16 v[34:37], v[240:243], v[196:199], v[34:37]
	v_mfma_f32_16x16x32_bf16 v[26:29], v[232:235], v[204:207], v[26:29]
	v_mfma_f32_16x16x32_bf16 v[18:21], v[240:243], v[204:207], v[18:21]
	v_mfma_f32_16x16x32_bf16 v[10:13], v[232:235], v[224:227], v[10:13]
	v_mfma_f32_16x16x32_bf16 v[2:5], v[240:243], v[224:227], v[2:5]
	s_setprio 0
	s_add_i32 s37, s37, 2
	s_add_u32 s16, s16, 0x100
	s_addc_u32 s17, s17, 0
	s_add_u32 s11, s11, 0x100
	s_addc_u32 s36, s36, 0
	s_cmp_gt_u32 s37, 29
	s_barrier
	s_cbranch_scc0 .LBB0_550
	s_mov_b64 s[0:1], s[78:79]
	s_load_dwordx2 s[0:1], s[0:1], 0xc0
	v_lshl_or_b32 v140, s10, 7, v146
	v_ashrrev_i32_e32 v141, 31, v140
	v_lshl_add_u32 v148, s14, 8, v144
	s_waitcnt lgkmcnt(0)
	v_lshl_add_u64 v[140:141], v[140:141], 1, s[0:1]
	s_mov_b64 s[0:1], 0x153b4000
	v_lshl_add_u64 v[140:141], v[140:141], 0, s[0:1]
	s_and_b64 vcc, exec, s[2:3]
	s_mov_b32 s10, s4
	s_mov_b32 s14, s6
	s_mov_b64 s[18:19], s[12:13]
	s_mov_b64 s[16:17], s[8:9]
	s_mov_b32 s98, 0xbfb8aa3b
	s_mov_b32 s99, 0xbfb8aa3b
	v_mad_i64_i32 v[200:201], s[100:101], v148, s95, v[140:141]
	v_add_u32_e32 v196, 0x10, v148
	v_mad_i64_i32 v[202:203], s[100:101], v196, s95, v[140:141]
	v_add_u32_e32 v196, 0x20, v148
	v_mad_i64_i32 v[204:205], s[100:101], v196, s95, v[140:141]
	v_add_u32_e32 v196, 0x30, v148
	v_mad_i64_i32 v[206:207], s[100:101], v196, s95, v[140:141]
	v_add_u32_e32 v196, 0x80, v148
	v_mad_i64_i32 v[208:209], s[100:101], v196, s95, v[140:141]
	v_add_u32_e32 v196, 0x90, v148
	v_mad_i64_i32 v[210:211], s[100:101], v196, s95, v[140:141]
	v_add_u32_e32 v196, 0xa0, v148
	v_mad_i64_i32 v[224:225], s[100:101], v196, s95, v[140:141]
	v_add_u32_e32 v196, 0xb0, v148
	v_mad_i64_i32 v[226:227], s[100:101], v196, s95, v[140:141]
	s_mov_b32 s100, 1.0
	s_mov_b32 s101, 1.0
	v_pk_mul_f32 v[184:185], v[126:127], s[98:99]
	v_pk_mul_f32 v[186:187], v[128:129], s[98:99]
	v_pk_mul_f32 v[188:189], v[118:119], s[98:99]
	v_pk_mul_f32 v[190:191], v[120:121], s[98:99]
	v_exp_f32_e32 v184, v184
	v_exp_f32_e32 v185, v185
	v_exp_f32_e32 v186, v186
	v_exp_f32_e32 v187, v187
	v_exp_f32_e32 v188, v188
	v_exp_f32_e32 v189, v189
	v_exp_f32_e32 v190, v190
	v_exp_f32_e32 v191, v191
	v_pk_add_f32 v[184:185], v[184:185], s[100:101]
	v_pk_add_f32 v[186:187], v[186:187], s[100:101]
	v_pk_add_f32 v[188:189], v[188:189], s[100:101]
	v_pk_add_f32 v[190:191], v[190:191], s[100:101]
	v_rcp_f32_e32 v184, v184
	v_rcp_f32_e32 v185, v185
	v_rcp_f32_e32 v186, v186
	v_rcp_f32_e32 v187, v187
	v_rcp_f32_e32 v188, v188
	v_rcp_f32_e32 v189, v189
	v_rcp_f32_e32 v190, v190
	v_rcp_f32_e32 v191, v191
	v_pk_mul_f32 v[184:185], v[126:127], v[184:185]
	v_pk_mul_f32 v[186:187], v[128:129], v[186:187]
	v_pk_mul_f32 v[188:189], v[118:119], v[188:189]
	v_pk_mul_f32 v[190:191], v[120:121], v[190:191]
	v_pk_mul_f32 v[184:185], v[122:123], v[184:185]
	v_pk_mul_f32 v[186:187], v[124:125], v[186:187]
	v_pk_mul_f32 v[188:189], v[114:115], v[188:189]
	v_pk_mul_f32 v[190:191], v[116:117], v[190:191]
	v_cvt_pk_bf16_f32 v192, v184, v185
	v_cvt_pk_bf16_f32 v193, v186, v187
	v_cvt_pk_bf16_f32 v194, v188, v189
	v_cvt_pk_bf16_f32 v195, v190, v191
	global_store_dwordx4 v[200:201], v[192:195], off
	v_pk_mul_f32 v[184:185], v[110:111], s[98:99]
	v_pk_mul_f32 v[186:187], v[112:113], s[98:99]
	v_pk_mul_f32 v[188:189], v[102:103], s[98:99]
; __device__ __forceinline__ unsigned cvt_pk_bf16(float lo, float hi) { unsigned r; asm("v_cvt_pk_bf16_f32 %0, %1, %2" : "=v"(r) : "v"(lo), "v"(hi)); return r; }
; __device__ __forceinline__ float silu_fast(float x) { return x * __builtin_amdgcn_rcpf(1.0f + __expf(-x)); }
;     __device__ __forceinline__ void operator()(const f32x4 (&acc)[2][2][4][2], const Unit& u, int wr, int wc, int fr, int fq) const {
;         const int row0 = u.pm * BM + wr * 64 + fr, col0 = u.pn * 128 + wc * 32 + 8 * fq;
; #pragma unroll
;         for (int ai = 0; ai < 2; ++ai)
; #pragma unroll
;             for (int m = 0; m < 4; ++m) {
;                 bf16_t* rowp = O + (size_t)(row0 + ai * HALF + m * 16) * DFF + col0;
;                 const f32x4 g0 = acc[ai][0][m][0], g1 = acc[ai][0][m][1], u0 = acc[ai][1][m][0], u1 = acc[ai][1][m][1];
;                 u32x4 w;
;                 w.x = cvt_pk_bf16(silu_fast(g0[0]) * u0[0], silu_fast(g0[1]) * u0[1]);
;                 w.y = cvt_pk_bf16(silu_fast(g0[2]) * u0[2], silu_fast(g0[3]) * u0[3]);
;                 w.z = cvt_pk_bf16(silu_fast(g1[0]) * u1[0], silu_fast(g1[1]) * u1[1]);
;                 w.w = cvt_pk_bf16(silu_fast(g1[2]) * u1[2], silu_fast(g1[3]) * u1[3]);
;                 *(u32x4*)rowp = w;
;             }
;     }
	v_pk_mul_f32 v[190:191], v[104:105], s[98:99]
	v_exp_f32_e32 v184, v184
	v_exp_f32_e32 v185, v185
	v_exp_f32_e32 v186, v186
	v_exp_f32_e32 v187, v187
	v_exp_f32_e32 v188, v188
	v_exp_f32_e32 v189, v189
	v_exp_f32_e32 v190, v190
	v_exp_f32_e32 v191, v191
	v_pk_add_f32 v[184:185], v[184:185], s[100:101]
	v_pk_add_f32 v[186:187], v[186:187], s[100:101]
	v_pk_add_f32 v[188:189], v[188:189], s[100:101]
	v_pk_add_f32 v[190:191], v[190:191], s[100:101]
	v_rcp_f32_e32 v184, v184
	v_rcp_f32_e32 v185, v185
	v_rcp_f32_e32 v186, v186
	v_rcp_f32_e32 v187, v187
	v_rcp_f32_e32 v188, v188
	v_rcp_f32_e32 v189, v189
	v_rcp_f32_e32 v190, v190
	v_rcp_f32_e32 v191, v191
	v_pk_mul_f32 v[184:185], v[110:111], v[184:185]
	v_pk_mul_f32 v[186:187], v[112:113], v[186:187]
	v_pk_mul_f32 v[188:189], v[102:103], v[188:189]
	v_pk_mul_f32 v[190:191], v[104:105], v[190:191]
	v_pk_mul_f32 v[184:185], v[106:107], v[184:185]
	v_pk_mul_f32 v[186:187], v[108:109], v[186:187]
	v_pk_mul_f32 v[188:189], v[98:99], v[188:189]
	v_pk_mul_f32 v[190:191], v[100:101], v[190:191]
	v_cvt_pk_bf16_f32 v192, v184, v185
	v_cvt_pk_bf16_f32 v193, v186, v187
	v_cvt_pk_bf16_f32 v194, v188, v189
	v_cvt_pk_bf16_f32 v195, v190, v191
	global_store_dwordx4 v[202:203], v[192:195], off
	v_pk_mul_f32 v[184:185], v[94:95], s[98:99]
	v_pk_mul_f32 v[186:187], v[96:97], s[98:99]
	v_pk_mul_f32 v[188:189], v[86:87], s[98:99]
	v_pk_mul_f32 v[190:191], v[88:89], s[98:99]
	v_exp_f32_e32 v184, v184
	v_exp_f32_e32 v185, v185
	v_exp_f32_e32 v186, v186
	v_exp_f32_e32 v187, v187
	v_exp_f32_e32 v188, v188
	v_exp_f32_e32 v189, v189
	v_exp_f32_e32 v190, v190
	v_exp_f32_e32 v191, v191
	v_pk_add_f32 v[184:185], v[184:185], s[100:101]
	v_pk_add_f32 v[186:187], v[186:187], s[100:101]
	v_pk_add_f32 v[188:189], v[188:189], s[100:101]
	v_pk_add_f32 v[190:191], v[190:191], s[100:101]
	v_rcp_f32_e32 v184, v184
	v_rcp_f32_e32 v185, v185
	v_rcp_f32_e32 v186, v186
	v_rcp_f32_e32 v187, v187
	v_rcp_f32_e32 v188, v188
	v_rcp_f32_e32 v189, v189
	v_rcp_f32_e32 v190, v190
	v_rcp_f32_e32 v191, v191
	v_pk_mul_f32 v[184:185], v[94:95], v[184:185]
	v_pk_mul_f32 v[186:187], v[96:97], v[186:187]
	v_pk_mul_f32 v[188:189], v[86:87], v[188:189]
	v_pk_mul_f32 v[190:191], v[88:89], v[190:191]
	v_pk_mul_f32 v[184:185], v[90:91], v[184:185]
	v_pk_mul_f32 v[186:187], v[92:93], v[186:187]
	v_pk_mul_f32 v[188:189], v[82:83], v[188:189]
	v_pk_mul_f32 v[190:191], v[84:85], v[190:191]
	v_cvt_pk_bf16_f32 v192, v184, v185
	v_cvt_pk_bf16_f32 v193, v186, v187
	v_cvt_pk_bf16_f32 v194, v188, v189
	v_cvt_pk_bf16_f32 v195, v190, v191
	global_store_dwordx4 v[204:205], v[192:195], off
	v_pk_mul_f32 v[184:185], v[78:79], s[98:99]
	v_pk_mul_f32 v[186:187], v[80:81], s[98:99]
	v_pk_mul_f32 v[188:189], v[70:71], s[98:99]
	v_pk_mul_f32 v[190:191], v[72:73], s[98:99]
	v_exp_f32_e32 v184, v184
	v_exp_f32_e32 v185, v185
	v_exp_f32_e32 v186, v186
	v_exp_f32_e32 v187, v187
	v_exp_f32_e32 v188, v188
	v_exp_f32_e32 v189, v189
	v_exp_f32_e32 v190, v190
	v_exp_f32_e32 v191, v191
	v_pk_add_f32 v[184:185], v[184:185], s[100:101]
	v_pk_add_f32 v[186:187], v[186:187], s[100:101]
	v_pk_add_f32 v[188:189], v[188:189], s[100:101]
	v_pk_add_f32 v[190:191], v[190:191], s[100:101]
	v_rcp_f32_e32 v184, v184
	v_rcp_f32_e32 v185, v185
	v_rcp_f32_e32 v186, v186
	v_rcp_f32_e32 v187, v187
	v_rcp_f32_e32 v188, v188
	v_rcp_f32_e32 v189, v189
	v_rcp_f32_e32 v190, v190
	v_rcp_f32_e32 v191, v191
	v_pk_mul_f32 v[184:185], v[78:79], v[184:185]
	v_pk_mul_f32 v[186:187], v[80:81], v[186:187]
	v_pk_mul_f32 v[188:189], v[70:71], v[188:189]
	v_pk_mul_f32 v[190:191], v[72:73], v[190:191]
	v_pk_mul_f32 v[184:185], v[74:75], v[184:185]
	v_pk_mul_f32 v[186:187], v[76:77], v[186:187]
	v_pk_mul_f32 v[188:189], v[66:67], v[188:189]
	v_pk_mul_f32 v[190:191], v[68:69], v[190:191]
	v_cvt_pk_bf16_f32 v192, v184, v185
	v_cvt_pk_bf16_f32 v193, v186, v187
	v_cvt_pk_bf16_f32 v194, v188, v189
	v_cvt_pk_bf16_f32 v195, v190, v191
	global_store_dwordx4 v[206:207], v[192:195], off
	v_pk_mul_f32 v[184:185], v[62:63], s[98:99]
	v_pk_mul_f32 v[186:187], v[64:65], s[98:99]
	v_pk_mul_f32 v[188:189], v[54:55], s[98:99]
	v_pk_mul_f32 v[190:191], v[56:57], s[98:99]
	v_exp_f32_e32 v184, v184
	v_exp_f32_e32 v185, v185
	v_exp_f32_e32 v186, v186
	v_exp_f32_e32 v187, v187
	v_exp_f32_e32 v188, v188
	v_exp_f32_e32 v189, v189
	v_exp_f32_e32 v190, v190
	v_exp_f32_e32 v191, v191
	v_pk_add_f32 v[184:185], v[184:185], s[100:101]
	v_pk_add_f32 v[186:187], v[186:187], s[100:101]
	v_pk_add_f32 v[188:189], v[188:189], s[100:101]
	v_pk_add_f32 v[190:191], v[190:191], s[100:101]
	v_rcp_f32_e32 v184, v184
	v_rcp_f32_e32 v185, v185
	v_rcp_f32_e32 v186, v186
	v_rcp_f32_e32 v187, v187
	v_rcp_f32_e32 v188, v188
	v_rcp_f32_e32 v189, v189
	v_rcp_f32_e32 v190, v190
	v_rcp_f32_e32 v191, v191
; __device__ __forceinline__ unsigned cvt_pk_bf16(float lo, float hi) { unsigned r; asm("v_cvt_pk_bf16_f32 %0, %1, %2" : "=v"(r) : "v"(lo), "v"(hi)); return r; }
; __device__ __forceinline__ float silu_fast(float x) { return x * __builtin_amdgcn_rcpf(1.0f + __expf(-x)); }
; #define PG8_WAIT_V(n) asm volatile("s_waitcnt vmcnt(" #n ")" ::: "memory")
; #define PG8_BAR __builtin_amdgcn_s_barrier()
;     __device__ __forceinline__ void operator()(const f32x4 (&acc)[2][2][4][2], const Unit& u, int wr, int wc, int fr, int fq) const {
;         const int row0 = u.pm * BM + wr * 64 + fr, col0 = u.pn * 128 + wc * 32 + 8 * fq;
; #pragma unroll
;         for (int ai = 0; ai < 2; ++ai)
; #pragma unroll
;             for (int m = 0; m < 4; ++m) {
;                 bf16_t* rowp = O + (size_t)(row0 + ai * HALF + m * 16) * DFF + col0;
;                 const f32x4 g0 = acc[ai][0][m][0], g1 = acc[ai][0][m][1], u0 = acc[ai][1][m][0], u1 = acc[ai][1][m][1];
;                 u32x4 w;
;                 w.x = cvt_pk_bf16(silu_fast(g0[0]) * u0[0], silu_fast(g0[1]) * u0[1]);
;                 w.y = cvt_pk_bf16(silu_fast(g0[2]) * u0[2], silu_fast(g0[3]) * u0[3]);
;                 w.z = cvt_pk_bf16(silu_fast(g1[0]) * u1[0], silu_fast(g1[1]) * u1[1]);
;                 w.w = cvt_pk_bf16(silu_fast(g1[2]) * u1[2], silu_fast(g1[3]) * u1[3]);
;                 *(u32x4*)rowp = w;
;             }
;     }
; template <class Epi>
; __device__ __forceinline__ void gemm_phase(LAS unsigned char* lds, const Gemm g, const Order& S, KP kp, int code, int wv) {
;     ...
;         if (!has_next) break;
; #pragma unroll
;         for (int a = 0; a < 2; ++a)
; #pragma unroll
;             for (int b = 0; b < 2; ++b)
; #pragma unroll
;                 for (int m = 0; m < 4; ++m)
; #pragma unroll
;                     for (int n = 0; n < 2; ++n) acc[a][b][m][n] = (f32x4){0.f, 0.f, 0.f, 0.f};
;         cur = nxt; cA = nA; cB = nB; ++ui;
;     }
;     PG8_WAIT_V(0);
;     if (wr == 0) PG8_BAR;
;     PG8_BAR;
	v_pk_mul_f32 v[184:185], v[62:63], v[184:185]
	v_pk_mul_f32 v[186:187], v[64:65], v[186:187]
	v_pk_mul_f32 v[188:189], v[54:55], v[188:189]
	v_pk_mul_f32 v[190:191], v[56:57], v[190:191]
	v_pk_mul_f32 v[184:185], v[58:59], v[184:185]
	v_pk_mul_f32 v[186:187], v[60:61], v[186:187]
	v_pk_mul_f32 v[188:189], v[50:51], v[188:189]
	v_pk_mul_f32 v[190:191], v[52:53], v[190:191]
	v_cvt_pk_bf16_f32 v192, v184, v185
	v_cvt_pk_bf16_f32 v193, v186, v187
	v_cvt_pk_bf16_f32 v194, v188, v189
	v_cvt_pk_bf16_f32 v195, v190, v191
	global_store_dwordx4 v[208:209], v[192:195], off
	v_pk_mul_f32 v[184:185], v[46:47], s[98:99]
	v_pk_mul_f32 v[186:187], v[48:49], s[98:99]
	v_pk_mul_f32 v[188:189], v[38:39], s[98:99]
	v_pk_mul_f32 v[190:191], v[40:41], s[98:99]
	v_exp_f32_e32 v184, v184
	v_exp_f32_e32 v185, v185
	v_exp_f32_e32 v186, v186
	v_exp_f32_e32 v187, v187
	v_exp_f32_e32 v188, v188
	v_exp_f32_e32 v189, v189
	v_exp_f32_e32 v190, v190
	v_exp_f32_e32 v191, v191
	v_pk_add_f32 v[184:185], v[184:185], s[100:101]
	v_pk_add_f32 v[186:187], v[186:187], s[100:101]
	v_pk_add_f32 v[188:189], v[188:189], s[100:101]
	v_pk_add_f32 v[190:191], v[190:191], s[100:101]
	v_rcp_f32_e32 v184, v184
	v_rcp_f32_e32 v185, v185
	v_rcp_f32_e32 v186, v186
	v_rcp_f32_e32 v187, v187
	v_rcp_f32_e32 v188, v188
	v_rcp_f32_e32 v189, v189
	v_rcp_f32_e32 v190, v190
	v_rcp_f32_e32 v191, v191
	v_pk_mul_f32 v[184:185], v[46:47], v[184:185]
	v_pk_mul_f32 v[186:187], v[48:49], v[186:187]
	v_pk_mul_f32 v[188:189], v[38:39], v[188:189]
	v_pk_mul_f32 v[190:191], v[40:41], v[190:191]
	v_pk_mul_f32 v[184:185], v[42:43], v[184:185]
	v_pk_mul_f32 v[186:187], v[44:45], v[186:187]
	v_pk_mul_f32 v[188:189], v[34:35], v[188:189]
	v_pk_mul_f32 v[190:191], v[36:37], v[190:191]
	v_cvt_pk_bf16_f32 v192, v184, v185
	v_cvt_pk_bf16_f32 v193, v186, v187
	v_cvt_pk_bf16_f32 v194, v188, v189
	v_cvt_pk_bf16_f32 v195, v190, v191
	global_store_dwordx4 v[210:211], v[192:195], off
	v_pk_mul_f32 v[184:185], v[30:31], s[98:99]
	v_pk_mul_f32 v[186:187], v[32:33], s[98:99]
	v_pk_mul_f32 v[188:189], v[22:23], s[98:99]
	v_pk_mul_f32 v[190:191], v[24:25], s[98:99]
	v_exp_f32_e32 v184, v184
	v_exp_f32_e32 v185, v185
	v_exp_f32_e32 v186, v186
	v_exp_f32_e32 v187, v187
	v_exp_f32_e32 v188, v188
	v_exp_f32_e32 v189, v189
	v_exp_f32_e32 v190, v190
	v_exp_f32_e32 v191, v191
	v_pk_add_f32 v[184:185], v[184:185], s[100:101]
	v_pk_add_f32 v[186:187], v[186:187], s[100:101]
	v_pk_add_f32 v[188:189], v[188:189], s[100:101]
	v_pk_add_f32 v[190:191], v[190:191], s[100:101]
	v_rcp_f32_e32 v184, v184
	v_rcp_f32_e32 v185, v185
	v_rcp_f32_e32 v186, v186
	v_rcp_f32_e32 v187, v187
	v_rcp_f32_e32 v188, v188
	v_rcp_f32_e32 v189, v189
	v_rcp_f32_e32 v190, v190
	v_rcp_f32_e32 v191, v191
	v_pk_mul_f32 v[184:185], v[30:31], v[184:185]
	v_pk_mul_f32 v[186:187], v[32:33], v[186:187]
	v_pk_mul_f32 v[188:189], v[22:23], v[188:189]
	v_pk_mul_f32 v[190:191], v[24:25], v[190:191]
	v_pk_mul_f32 v[184:185], v[26:27], v[184:185]
	v_pk_mul_f32 v[186:187], v[28:29], v[186:187]
	v_pk_mul_f32 v[188:189], v[18:19], v[188:189]
	v_pk_mul_f32 v[190:191], v[20:21], v[190:191]
	v_cvt_pk_bf16_f32 v192, v184, v185
	v_cvt_pk_bf16_f32 v193, v186, v187
	v_cvt_pk_bf16_f32 v194, v188, v189
	v_cvt_pk_bf16_f32 v195, v190, v191
	global_store_dwordx4 v[224:225], v[192:195], off
	v_pk_mul_f32 v[184:185], v[14:15], s[98:99]
	v_pk_mul_f32 v[186:187], v[16:17], s[98:99]
	v_pk_mul_f32 v[188:189], v[6:7], s[98:99]
	v_pk_mul_f32 v[190:191], v[8:9], s[98:99]
	v_exp_f32_e32 v184, v184
	v_exp_f32_e32 v185, v185
	v_exp_f32_e32 v186, v186
	v_exp_f32_e32 v187, v187
	v_exp_f32_e32 v188, v188
	v_exp_f32_e32 v189, v189
	v_exp_f32_e32 v190, v190
	v_exp_f32_e32 v191, v191
	v_pk_add_f32 v[184:185], v[184:185], s[100:101]
	v_pk_add_f32 v[186:187], v[186:187], s[100:101]
	v_pk_add_f32 v[188:189], v[188:189], s[100:101]
	v_pk_add_f32 v[190:191], v[190:191], s[100:101]
	v_rcp_f32_e32 v184, v184
	v_rcp_f32_e32 v185, v185
	v_rcp_f32_e32 v186, v186
	v_rcp_f32_e32 v187, v187
	v_rcp_f32_e32 v188, v188
	v_rcp_f32_e32 v189, v189
	v_rcp_f32_e32 v190, v190
	v_rcp_f32_e32 v191, v191
	v_pk_mul_f32 v[184:185], v[14:15], v[184:185]
	v_pk_mul_f32 v[186:187], v[16:17], v[186:187]
	v_pk_mul_f32 v[188:189], v[6:7], v[188:189]
	v_pk_mul_f32 v[190:191], v[8:9], v[190:191]
	v_pk_mul_f32 v[184:185], v[10:11], v[184:185]
	v_pk_mul_f32 v[186:187], v[12:13], v[186:187]
	v_pk_mul_f32 v[188:189], v[2:3], v[188:189]
	v_pk_mul_f32 v[190:191], v[4:5], v[190:191]
	v_cvt_pk_bf16_f32 v192, v184, v185
	v_cvt_pk_bf16_f32 v193, v186, v187
	v_cvt_pk_bf16_f32 v194, v188, v189
	v_cvt_pk_bf16_f32 v195, v190, v191
	global_store_dwordx4 v[226:227], v[192:195], off
	s_cbranch_vccz .LBB0_547
	s_waitcnt vmcnt(0)
	s_cmpk_gt_u32 s23, 0xff
	s_mov_b32 s35, 0x3f2aaaab
	s_cbranch_scc1 .LBB0_554
	s_barrier
